# mix2 phase rewritten: contiguous 64-token block per WG, x row reuse, 8-deep load prefetch
# speedup vs baseline: 1.1195x; 1.1195x over previous
.LBB0_222:
	s_mov_b64 s[4:5], s[0:1]
	s_load_dword s3, s[4:5], 0xe8
	s_waitcnt lgkmcnt(0)
	s_cmp_gt_i32 s3, 2
	s_cbranch_scc1 .LBB0_230
	s_mov_b64 s[4:5], s[0:1]
	s_load_dword s3, s[4:5], 0xec
	s_waitcnt lgkmcnt(0)
	s_cmp_lt_i32 s3, 3
	s_cbranch_scc1 .LBB0_230
	s_cmp_eq_u32 s24, 0x100
	s_cbranch_scc0 .Lmix2_orig
	s_load_dwordx2 s[16:17], s[0:1], 0x8
	s_load_dwordx2 s[18:19], s[0:1], 0x0
	s_load_dwordx2 s[20:21], s[0:1], 0xe0
	v_lshlrev_b32_e32 v1, 4, v190
	v_lshlrev_b32_e32 v2, 3, v190
	s_lshl_b32 s3, s2, 19
	s_lshl_b32 s22, s2, 18
	s_waitcnt lgkmcnt(0)
	s_add_u32 s12, s16, 0x2000
	s_addc_u32 s13, s17, 0
	global_load_dwordx4 v[4:7], v1, s[12:13]
	s_add_u32 s12, s16, 0x8000
	s_addc_u32 s13, s17, 0
	global_load_dwordx4 v[8:11], v1, s[12:13]
	s_add_u32 s12, s16, 0xa000
	s_addc_u32 s13, s17, 0
	global_load_dwordx4 v[12:15], v1, s[12:13]
	s_add_u32 s4, s18, s3
	s_addc_u32 s5, s19, 0
	s_add_u32 s6, s20, 0x8100000
	s_addc_u32 s7, s21, 0
	s_add_u32 s6, s6, s22
	s_addc_u32 s7, s7, 0
	s_add_u32 s8, s6, 0x4000000
	s_addc_u32 s9, s7, 0
	s_add_u32 s10, s6, 0x8000000
	s_addc_u32 s11, s7, 0
	v_mov_b32_e32 v16, 0
	v_mov_b32_e32 v17, 0
	v_mov_b32_e32 v18, 0
	v_mov_b32_e32 v19, 0
	s_and_b32 s3, s2, 63
	s_cmp_eq_u32 s3, 0
	s_cbranch_scc1 .Lmix2_noprev
	s_sub_u32 s22, s4, 0x2000
	s_subb_u32 s23, s5, 0
	global_load_dwordx4 v[16:19], v1, s[22:23]
.Lmix2_noprev:
	global_load_dwordx4 v[20:23], v1, s[4:5]
	s_add_u32 s4, s4, 0x2000
	s_addc_u32 s5, s5, 0
	global_load_dwordx4 v[24:27], v1, s[4:5]
	s_add_u32 s4, s4, 0x2000
	s_addc_u32 s5, s5, 0
	global_load_dwordx4 v[28:31], v1, s[4:5]
	s_add_u32 s4, s4, 0x2000
	s_addc_u32 s5, s5, 0
	global_load_dwordx4 v[32:35], v1, s[4:5]
	s_add_u32 s4, s4, 0x2000
	s_addc_u32 s5, s5, 0
	global_load_dwordx4 v[36:39], v1, s[4:5]
	s_add_u32 s4, s4, 0x2000
	s_addc_u32 s5, s5, 0
	global_load_dwordx4 v[40:43], v1, s[4:5]
	s_add_u32 s4, s4, 0x2000
	s_addc_u32 s5, s5, 0
	global_load_dwordx4 v[44:47], v1, s[4:5]
	s_add_u32 s4, s4, 0x2000
	s_addc_u32 s5, s5, 0
	global_load_dwordx4 v[48:51], v1, s[4:5]
	s_add_u32 s4, s4, 0x2000
	s_addc_u32 s5, s5, 0
	global_load_dwordx4 v[52:55], v1, s[4:5]
	s_add_u32 s4, s4, 0x2000
	s_addc_u32 s5, s5, 0
	global_load_dwordx4 v[56:59], v1, s[4:5]
	s_add_u32 s4, s4, 0x2000
	s_addc_u32 s5, s5, 0
	global_load_dwordx4 v[60:63], v1, s[4:5]
	s_add_u32 s4, s4, 0x2000
	s_addc_u32 s5, s5, 0
	global_load_dwordx4 v[64:67], v1, s[4:5]
	s_add_u32 s4, s4, 0x2000
	s_addc_u32 s5, s5, 0
	global_load_dwordx4 v[68:71], v1, s[4:5]
	s_add_u32 s4, s4, 0x2000
	s_addc_u32 s5, s5, 0
	global_load_dwordx4 v[72:75], v1, s[4:5]
	s_add_u32 s4, s4, 0x2000
	s_addc_u32 s5, s5, 0
	global_load_dwordx4 v[76:79], v1, s[4:5]
	s_add_u32 s4, s4, 0x2000
	s_addc_u32 s5, s5, 0
	global_load_dwordx4 v[80:83], v1, s[4:5]
	s_add_u32 s4, s4, 0x2000
	s_addc_u32 s5, s5, 0
	s_waitcnt vmcnt(15)
	v_sub_f32_e32 v84, v16, v20
	v_sub_f32_e32 v85, v17, v21
	v_sub_f32_e32 v86, v18, v22
	v_sub_f32_e32 v87, v19, v23
	v_pk_fma_f32 v[88:89], v[84:85], v[4:5], v[20:21]
	v_pk_fma_f32 v[90:91], v[86:87], v[6:7], v[22:23]
	v_pk_fma_f32 v[92:93], v[84:85], v[8:9], v[20:21]
	v_pk_fma_f32 v[94:95], v[86:87], v[10:11], v[22:23]
	v_pk_fma_f32 v[96:97], v[84:85], v[12:13], v[20:21]
	v_pk_fma_f32 v[98:99], v[86:87], v[14:15], v[22:23]
	v_cvt_pk_bf16_f32 v100, v88, v89
	v_cvt_pk_bf16_f32 v101, v90, v91
	v_cvt_pk_bf16_f32 v102, v92, v93
	v_cvt_pk_bf16_f32 v103, v94, v95
	v_cvt_pk_bf16_f32 v104, v96, v97
	v_cvt_pk_bf16_f32 v105, v98, v99
	global_store_dwordx2 v2, v[100:101], s[6:7]
	global_store_dwordx2 v2, v[102:103], s[8:9]
	global_store_dwordx2 v2, v[104:105], s[10:11]
	s_add_u32 s6, s6, 0x1000
	s_addc_u32 s7, s7, 0
	s_add_u32 s8, s8, 0x1000
	s_addc_u32 s9, s9, 0
	s_add_u32 s10, s10, 0x1000
	s_addc_u32 s11, s11, 0
	s_waitcnt vmcnt(17)
	v_sub_f32_e32 v84, v20, v24
	v_sub_f32_e32 v85, v21, v25
	v_sub_f32_e32 v86, v22, v26
	v_sub_f32_e32 v87, v23, v27
	v_pk_fma_f32 v[88:89], v[84:85], v[4:5], v[24:25]
	v_pk_fma_f32 v[90:91], v[86:87], v[6:7], v[26:27]
	v_pk_fma_f32 v[92:93], v[84:85], v[8:9], v[24:25]
	v_pk_fma_f32 v[94:95], v[86:87], v[10:11], v[26:27]
	v_pk_fma_f32 v[96:97], v[84:85], v[12:13], v[24:25]
	v_pk_fma_f32 v[98:99], v[86:87], v[14:15], v[26:27]
	v_cvt_pk_bf16_f32 v106, v88, v89
	v_cvt_pk_bf16_f32 v107, v90, v91
	v_cvt_pk_bf16_f32 v108, v92, v93
	v_cvt_pk_bf16_f32 v109, v94, v95
	v_cvt_pk_bf16_f32 v110, v96, v97
	v_cvt_pk_bf16_f32 v111, v98, v99
	global_store_dwordx2 v2, v[106:107], s[6:7]
	global_store_dwordx2 v2, v[108:109], s[8:9]
	global_store_dwordx2 v2, v[110:111], s[10:11]
	s_add_u32 s6, s6, 0x1000
	s_addc_u32 s7, s7, 0
	s_add_u32 s8, s8, 0x1000
	s_addc_u32 s9, s9, 0
	s_add_u32 s10, s10, 0x1000
	s_addc_u32 s11, s11, 0
	s_waitcnt vmcnt(19)
	v_sub_f32_e32 v84, v24, v28
	v_sub_f32_e32 v85, v25, v29
	v_sub_f32_e32 v86, v26, v30
	v_sub_f32_e32 v87, v27, v31
	v_pk_fma_f32 v[88:89], v[84:85], v[4:5], v[28:29]
	v_pk_fma_f32 v[90:91], v[86:87], v[6:7], v[30:31]
	v_pk_fma_f32 v[92:93], v[84:85], v[8:9], v[28:29]
	v_pk_fma_f32 v[94:95], v[86:87], v[10:11], v[30:31]
	v_pk_fma_f32 v[96:97], v[84:85], v[12:13], v[28:29]
	v_pk_fma_f32 v[98:99], v[86:87], v[14:15], v[30:31]
	v_cvt_pk_bf16_f32 v100, v88, v89
	v_cvt_pk_bf16_f32 v101, v90, v91
	v_cvt_pk_bf16_f32 v102, v92, v93
	v_cvt_pk_bf16_f32 v103, v94, v95
	v_cvt_pk_bf16_f32 v104, v96, v97
	v_cvt_pk_bf16_f32 v105, v98, v99
	global_store_dwordx2 v2, v[100:101], s[6:7]
	global_store_dwordx2 v2, v[102:103], s[8:9]
	global_store_dwordx2 v2, v[104:105], s[10:11]
	s_add_u32 s6, s6, 0x1000
	s_addc_u32 s7, s7, 0
	s_add_u32 s8, s8, 0x1000
	s_addc_u32 s9, s9, 0
	s_add_u32 s10, s10, 0x1000
	s_addc_u32 s11, s11, 0
	s_waitcnt vmcnt(21)
	v_sub_f32_e32 v84, v28, v32
	v_sub_f32_e32 v85, v29, v33
	v_sub_f32_e32 v86, v30, v34
	v_sub_f32_e32 v87, v31, v35
	v_pk_fma_f32 v[88:89], v[84:85], v[4:5], v[32:33]
	v_pk_fma_f32 v[90:91], v[86:87], v[6:7], v[34:35]
	v_pk_fma_f32 v[92:93], v[84:85], v[8:9], v[32:33]
	v_pk_fma_f32 v[94:95], v[86:87], v[10:11], v[34:35]
	v_pk_fma_f32 v[96:97], v[84:85], v[12:13], v[32:33]
	v_pk_fma_f32 v[98:99], v[86:87], v[14:15], v[34:35]
	v_cvt_pk_bf16_f32 v106, v88, v89
	v_cvt_pk_bf16_f32 v107, v90, v91
	v_cvt_pk_bf16_f32 v108, v92, v93
	v_cvt_pk_bf16_f32 v109, v94, v95
	v_cvt_pk_bf16_f32 v110, v96, v97
	v_cvt_pk_bf16_f32 v111, v98, v99
	global_store_dwordx2 v2, v[106:107], s[6:7]
	global_store_dwordx2 v2, v[108:109], s[8:9]
	global_store_dwordx2 v2, v[110:111], s[10:11]
	s_add_u32 s6, s6, 0x1000
	s_addc_u32 s7, s7, 0
	s_add_u32 s8, s8, 0x1000
	s_addc_u32 s9, s9, 0
	s_add_u32 s10, s10, 0x1000
	s_addc_u32 s11, s11, 0
	s_waitcnt vmcnt(23)
	v_sub_f32_e32 v84, v32, v36
	v_sub_f32_e32 v85, v33, v37
	v_sub_f32_e32 v86, v34, v38
	v_sub_f32_e32 v87, v35, v39
	v_pk_fma_f32 v[88:89], v[84:85], v[4:5], v[36:37]
	v_pk_fma_f32 v[90:91], v[86:87], v[6:7], v[38:39]
	v_pk_fma_f32 v[92:93], v[84:85], v[8:9], v[36:37]
	v_pk_fma_f32 v[94:95], v[86:87], v[10:11], v[38:39]
	v_pk_fma_f32 v[96:97], v[84:85], v[12:13], v[36:37]
	v_pk_fma_f32 v[98:99], v[86:87], v[14:15], v[38:39]
	v_cvt_pk_bf16_f32 v100, v88, v89
	v_cvt_pk_bf16_f32 v101, v90, v91
	v_cvt_pk_bf16_f32 v102, v92, v93
	v_cvt_pk_bf16_f32 v103, v94, v95
	v_cvt_pk_bf16_f32 v104, v96, v97
	v_cvt_pk_bf16_f32 v105, v98, v99
	global_store_dwordx2 v2, v[100:101], s[6:7]
	global_store_dwordx2 v2, v[102:103], s[8:9]
	global_store_dwordx2 v2, v[104:105], s[10:11]
	s_add_u32 s6, s6, 0x1000
	s_addc_u32 s7, s7, 0
	s_add_u32 s8, s8, 0x1000
	s_addc_u32 s9, s9, 0
	s_add_u32 s10, s10, 0x1000
	s_addc_u32 s11, s11, 0
	s_waitcnt vmcnt(25)
	v_sub_f32_e32 v84, v36, v40
	v_sub_f32_e32 v85, v37, v41
	v_sub_f32_e32 v86, v38, v42
	v_sub_f32_e32 v87, v39, v43
	v_pk_fma_f32 v[88:89], v[84:85], v[4:5], v[40:41]
	v_pk_fma_f32 v[90:91], v[86:87], v[6:7], v[42:43]
	v_pk_fma_f32 v[92:93], v[84:85], v[8:9], v[40:41]
	v_pk_fma_f32 v[94:95], v[86:87], v[10:11], v[42:43]
	v_pk_fma_f32 v[96:97], v[84:85], v[12:13], v[40:41]
	v_pk_fma_f32 v[98:99], v[86:87], v[14:15], v[42:43]
	v_cvt_pk_bf16_f32 v106, v88, v89
	v_cvt_pk_bf16_f32 v107, v90, v91
	v_cvt_pk_bf16_f32 v108, v92, v93
	v_cvt_pk_bf16_f32 v109, v94, v95
	v_cvt_pk_bf16_f32 v110, v96, v97
	v_cvt_pk_bf16_f32 v111, v98, v99
	global_store_dwordx2 v2, v[106:107], s[6:7]
	global_store_dwordx2 v2, v[108:109], s[8:9]
	global_store_dwordx2 v2, v[110:111], s[10:11]
	s_add_u32 s6, s6, 0x1000
	s_addc_u32 s7, s7, 0
	s_add_u32 s8, s8, 0x1000
	s_addc_u32 s9, s9, 0
	s_add_u32 s10, s10, 0x1000
	s_addc_u32 s11, s11, 0
	s_waitcnt vmcnt(27)
	v_sub_f32_e32 v84, v40, v44
	v_sub_f32_e32 v85, v41, v45
	v_sub_f32_e32 v86, v42, v46
	v_sub_f32_e32 v87, v43, v47
	v_pk_fma_f32 v[88:89], v[84:85], v[4:5], v[44:45]
	v_pk_fma_f32 v[90:91], v[86:87], v[6:7], v[46:47]
	v_pk_fma_f32 v[92:93], v[84:85], v[8:9], v[44:45]
	v_pk_fma_f32 v[94:95], v[86:87], v[10:11], v[46:47]
	v_pk_fma_f32 v[96:97], v[84:85], v[12:13], v[44:45]
	v_pk_fma_f32 v[98:99], v[86:87], v[14:15], v[46:47]
	v_cvt_pk_bf16_f32 v100, v88, v89
	v_cvt_pk_bf16_f32 v101, v90, v91
	v_cvt_pk_bf16_f32 v102, v92, v93
	v_cvt_pk_bf16_f32 v103, v94, v95
	v_cvt_pk_bf16_f32 v104, v96, v97
	v_cvt_pk_bf16_f32 v105, v98, v99
	global_store_dwordx2 v2, v[100:101], s[6:7]
	global_store_dwordx2 v2, v[102:103], s[8:9]
	global_store_dwordx2 v2, v[104:105], s[10:11]
	s_add_u32 s6, s6, 0x1000
	s_addc_u32 s7, s7, 0
	s_add_u32 s8, s8, 0x1000
	s_addc_u32 s9, s9, 0
	s_add_u32 s10, s10, 0x1000
	s_addc_u32 s11, s11, 0
	s_waitcnt vmcnt(29)
	v_sub_f32_e32 v84, v44, v48
	v_sub_f32_e32 v85, v45, v49
	v_sub_f32_e32 v86, v46, v50
	v_sub_f32_e32 v87, v47, v51
	v_pk_fma_f32 v[88:89], v[84:85], v[4:5], v[48:49]
	v_pk_fma_f32 v[90:91], v[86:87], v[6:7], v[50:51]
	v_pk_fma_f32 v[92:93], v[84:85], v[8:9], v[48:49]
	v_pk_fma_f32 v[94:95], v[86:87], v[10:11], v[50:51]
	v_pk_fma_f32 v[96:97], v[84:85], v[12:13], v[48:49]
	v_pk_fma_f32 v[98:99], v[86:87], v[14:15], v[50:51]
	v_cvt_pk_bf16_f32 v106, v88, v89
	v_cvt_pk_bf16_f32 v107, v90, v91
	v_cvt_pk_bf16_f32 v108, v92, v93
	v_cvt_pk_bf16_f32 v109, v94, v95
	v_cvt_pk_bf16_f32 v110, v96, v97
	v_cvt_pk_bf16_f32 v111, v98, v99
	global_store_dwordx2 v2, v[106:107], s[6:7]
	global_store_dwordx2 v2, v[108:109], s[8:9]
	global_store_dwordx2 v2, v[110:111], s[10:11]
	s_add_u32 s6, s6, 0x1000
	s_addc_u32 s7, s7, 0
	s_add_u32 s8, s8, 0x1000
	s_addc_u32 s9, s9, 0
	s_add_u32 s10, s10, 0x1000
	s_addc_u32 s11, s11, 0
	v_mov_b32_e32 v16, v48
	v_mov_b32_e32 v17, v49
	v_mov_b32_e32 v18, v50
	v_mov_b32_e32 v19, v51
	global_load_dwordx4 v[20:23], v1, s[4:5]
	s_add_u32 s4, s4, 0x2000
	s_addc_u32 s5, s5, 0
	global_load_dwordx4 v[24:27], v1, s[4:5]
	s_add_u32 s4, s4, 0x2000
	s_addc_u32 s5, s5, 0
	global_load_dwordx4 v[28:31], v1, s[4:5]
	s_add_u32 s4, s4, 0x2000
	s_addc_u32 s5, s5, 0
	global_load_dwordx4 v[32:35], v1, s[4:5]
	s_add_u32 s4, s4, 0x2000
	s_addc_u32 s5, s5, 0
	global_load_dwordx4 v[36:39], v1, s[4:5]
	s_add_u32 s4, s4, 0x2000
	s_addc_u32 s5, s5, 0
	global_load_dwordx4 v[40:43], v1, s[4:5]
	s_add_u32 s4, s4, 0x2000
	s_addc_u32 s5, s5, 0
	global_load_dwordx4 v[44:47], v1, s[4:5]
	s_add_u32 s4, s4, 0x2000
	s_addc_u32 s5, s5, 0
	global_load_dwordx4 v[48:51], v1, s[4:5]
	s_add_u32 s4, s4, 0x2000
	s_addc_u32 s5, s5, 0
	s_waitcnt vmcnt(39)
	v_sub_f32_e32 v84, v16, v52
	v_sub_f32_e32 v85, v17, v53
	v_sub_f32_e32 v86, v18, v54
	v_sub_f32_e32 v87, v19, v55
	v_pk_fma_f32 v[88:89], v[84:85], v[4:5], v[52:53]
	v_pk_fma_f32 v[90:91], v[86:87], v[6:7], v[54:55]
	v_pk_fma_f32 v[92:93], v[84:85], v[8:9], v[52:53]
	v_pk_fma_f32 v[94:95], v[86:87], v[10:11], v[54:55]
	v_pk_fma_f32 v[96:97], v[84:85], v[12:13], v[52:53]
	v_pk_fma_f32 v[98:99], v[86:87], v[14:15], v[54:55]
	v_cvt_pk_bf16_f32 v100, v88, v89
	v_cvt_pk_bf16_f32 v101, v90, v91
	v_cvt_pk_bf16_f32 v102, v92, v93
	v_cvt_pk_bf16_f32 v103, v94, v95
	v_cvt_pk_bf16_f32 v104, v96, v97
	v_cvt_pk_bf16_f32 v105, v98, v99
	global_store_dwordx2 v2, v[100:101], s[6:7]
	global_store_dwordx2 v2, v[102:103], s[8:9]
	global_store_dwordx2 v2, v[104:105], s[10:11]
	s_add_u32 s6, s6, 0x1000
	s_addc_u32 s7, s7, 0
	s_add_u32 s8, s8, 0x1000
	s_addc_u32 s9, s9, 0
	s_add_u32 s10, s10, 0x1000
	s_addc_u32 s11, s11, 0
	s_waitcnt vmcnt(41)
	v_sub_f32_e32 v84, v52, v56
	v_sub_f32_e32 v85, v53, v57
	v_sub_f32_e32 v86, v54, v58
	v_sub_f32_e32 v87, v55, v59
	v_pk_fma_f32 v[88:89], v[84:85], v[4:5], v[56:57]
	v_pk_fma_f32 v[90:91], v[86:87], v[6:7], v[58:59]
	v_pk_fma_f32 v[92:93], v[84:85], v[8:9], v[56:57]
	v_pk_fma_f32 v[94:95], v[86:87], v[10:11], v[58:59]
	v_pk_fma_f32 v[96:97], v[84:85], v[12:13], v[56:57]
	v_pk_fma_f32 v[98:99], v[86:87], v[14:15], v[58:59]
	v_cvt_pk_bf16_f32 v106, v88, v89
	v_cvt_pk_bf16_f32 v107, v90, v91
	v_cvt_pk_bf16_f32 v108, v92, v93
	v_cvt_pk_bf16_f32 v109, v94, v95
	v_cvt_pk_bf16_f32 v110, v96, v97
	v_cvt_pk_bf16_f32 v111, v98, v99
	global_store_dwordx2 v2, v[106:107], s[6:7]
	global_store_dwordx2 v2, v[108:109], s[8:9]
	global_store_dwordx2 v2, v[110:111], s[10:11]
	s_add_u32 s6, s6, 0x1000
	s_addc_u32 s7, s7, 0
	s_add_u32 s8, s8, 0x1000
	s_addc_u32 s9, s9, 0
	s_add_u32 s10, s10, 0x1000
	s_addc_u32 s11, s11, 0
	s_waitcnt vmcnt(43)
	v_sub_f32_e32 v84, v56, v60
	v_sub_f32_e32 v85, v57, v61
	v_sub_f32_e32 v86, v58, v62
	v_sub_f32_e32 v87, v59, v63
	v_pk_fma_f32 v[88:89], v[84:85], v[4:5], v[60:61]
	v_pk_fma_f32 v[90:91], v[86:87], v[6:7], v[62:63]
	v_pk_fma_f32 v[92:93], v[84:85], v[8:9], v[60:61]
	v_pk_fma_f32 v[94:95], v[86:87], v[10:11], v[62:63]
	v_pk_fma_f32 v[96:97], v[84:85], v[12:13], v[60:61]
	v_pk_fma_f32 v[98:99], v[86:87], v[14:15], v[62:63]
	v_cvt_pk_bf16_f32 v100, v88, v89
	v_cvt_pk_bf16_f32 v101, v90, v91
	v_cvt_pk_bf16_f32 v102, v92, v93
	v_cvt_pk_bf16_f32 v103, v94, v95
	v_cvt_pk_bf16_f32 v104, v96, v97
	v_cvt_pk_bf16_f32 v105, v98, v99
	global_store_dwordx2 v2, v[100:101], s[6:7]
	global_store_dwordx2 v2, v[102:103], s[8:9]
	global_store_dwordx2 v2, v[104:105], s[10:11]
	s_add_u32 s6, s6, 0x1000
	s_addc_u32 s7, s7, 0
	s_add_u32 s8, s8, 0x1000
	s_addc_u32 s9, s9, 0
	s_add_u32 s10, s10, 0x1000
	s_addc_u32 s11, s11, 0
	s_waitcnt vmcnt(45)
	v_sub_f32_e32 v84, v60, v64
	v_sub_f32_e32 v85, v61, v65
	v_sub_f32_e32 v86, v62, v66
	v_sub_f32_e32 v87, v63, v67
	v_pk_fma_f32 v[88:89], v[84:85], v[4:5], v[64:65]
	v_pk_fma_f32 v[90:91], v[86:87], v[6:7], v[66:67]
	v_pk_fma_f32 v[92:93], v[84:85], v[8:9], v[64:65]
	v_pk_fma_f32 v[94:95], v[86:87], v[10:11], v[66:67]
	v_pk_fma_f32 v[96:97], v[84:85], v[12:13], v[64:65]
	v_pk_fma_f32 v[98:99], v[86:87], v[14:15], v[66:67]
	v_cvt_pk_bf16_f32 v106, v88, v89
	v_cvt_pk_bf16_f32 v107, v90, v91
	v_cvt_pk_bf16_f32 v108, v92, v93
	v_cvt_pk_bf16_f32 v109, v94, v95
	v_cvt_pk_bf16_f32 v110, v96, v97
	v_cvt_pk_bf16_f32 v111, v98, v99
	global_store_dwordx2 v2, v[106:107], s[6:7]
	global_store_dwordx2 v2, v[108:109], s[8:9]
	global_store_dwordx2 v2, v[110:111], s[10:11]
	s_add_u32 s6, s6, 0x1000
	s_addc_u32 s7, s7, 0
	s_add_u32 s8, s8, 0x1000
	s_addc_u32 s9, s9, 0
	s_add_u32 s10, s10, 0x1000
	s_addc_u32 s11, s11, 0
	s_waitcnt vmcnt(47)
	v_sub_f32_e32 v84, v64, v68
	v_sub_f32_e32 v85, v65, v69
	v_sub_f32_e32 v86, v66, v70
	v_sub_f32_e32 v87, v67, v71
	v_pk_fma_f32 v[88:89], v[84:85], v[4:5], v[68:69]
	v_pk_fma_f32 v[90:91], v[86:87], v[6:7], v[70:71]
	v_pk_fma_f32 v[92:93], v[84:85], v[8:9], v[68:69]
	v_pk_fma_f32 v[94:95], v[86:87], v[10:11], v[70:71]
	v_pk_fma_f32 v[96:97], v[84:85], v[12:13], v[68:69]
	v_pk_fma_f32 v[98:99], v[86:87], v[14:15], v[70:71]
	v_cvt_pk_bf16_f32 v100, v88, v89
	v_cvt_pk_bf16_f32 v101, v90, v91
	v_cvt_pk_bf16_f32 v102, v92, v93
	v_cvt_pk_bf16_f32 v103, v94, v95
	v_cvt_pk_bf16_f32 v104, v96, v97
	v_cvt_pk_bf16_f32 v105, v98, v99
	global_store_dwordx2 v2, v[100:101], s[6:7]
	global_store_dwordx2 v2, v[102:103], s[8:9]
	global_store_dwordx2 v2, v[104:105], s[10:11]
	s_add_u32 s6, s6, 0x1000
	s_addc_u32 s7, s7, 0
	s_add_u32 s8, s8, 0x1000
	s_addc_u32 s9, s9, 0
	s_add_u32 s10, s10, 0x1000
	s_addc_u32 s11, s11, 0
	s_waitcnt vmcnt(49)
	v_sub_f32_e32 v84, v68, v72
	v_sub_f32_e32 v85, v69, v73
	v_sub_f32_e32 v86, v70, v74
	v_sub_f32_e32 v87, v71, v75
	v_pk_fma_f32 v[88:89], v[84:85], v[4:5], v[72:73]
	v_pk_fma_f32 v[90:91], v[86:87], v[6:7], v[74:75]
	v_pk_fma_f32 v[92:93], v[84:85], v[8:9], v[72:73]
	v_pk_fma_f32 v[94:95], v[86:87], v[10:11], v[74:75]
	v_pk_fma_f32 v[96:97], v[84:85], v[12:13], v[72:73]
	v_pk_fma_f32 v[98:99], v[86:87], v[14:15], v[74:75]
	v_cvt_pk_bf16_f32 v106, v88, v89
	v_cvt_pk_bf16_f32 v107, v90, v91
	v_cvt_pk_bf16_f32 v108, v92, v93
	v_cvt_pk_bf16_f32 v109, v94, v95
	v_cvt_pk_bf16_f32 v110, v96, v97
	v_cvt_pk_bf16_f32 v111, v98, v99
	global_store_dwordx2 v2, v[106:107], s[6:7]
	global_store_dwordx2 v2, v[108:109], s[8:9]
	global_store_dwordx2 v2, v[110:111], s[10:11]
	s_add_u32 s6, s6, 0x1000
	s_addc_u32 s7, s7, 0
	s_add_u32 s8, s8, 0x1000
	s_addc_u32 s9, s9, 0
	s_add_u32 s10, s10, 0x1000
	s_addc_u32 s11, s11, 0
	s_waitcnt vmcnt(51)
	v_sub_f32_e32 v84, v72, v76
	v_sub_f32_e32 v85, v73, v77
	v_sub_f32_e32 v86, v74, v78
	v_sub_f32_e32 v87, v75, v79
	v_pk_fma_f32 v[88:89], v[84:85], v[4:5], v[76:77]
	v_pk_fma_f32 v[90:91], v[86:87], v[6:7], v[78:79]
	v_pk_fma_f32 v[92:93], v[84:85], v[8:9], v[76:77]
	v_pk_fma_f32 v[94:95], v[86:87], v[10:11], v[78:79]
	v_pk_fma_f32 v[96:97], v[84:85], v[12:13], v[76:77]
	v_pk_fma_f32 v[98:99], v[86:87], v[14:15], v[78:79]
	v_cvt_pk_bf16_f32 v100, v88, v89
	v_cvt_pk_bf16_f32 v101, v90, v91
	v_cvt_pk_bf16_f32 v102, v92, v93
	v_cvt_pk_bf16_f32 v103, v94, v95
	v_cvt_pk_bf16_f32 v104, v96, v97
	v_cvt_pk_bf16_f32 v105, v98, v99
	global_store_dwordx2 v2, v[100:101], s[6:7]
	global_store_dwordx2 v2, v[102:103], s[8:9]
	global_store_dwordx2 v2, v[104:105], s[10:11]
	s_add_u32 s6, s6, 0x1000
	s_addc_u32 s7, s7, 0
	s_add_u32 s8, s8, 0x1000
	s_addc_u32 s9, s9, 0
	s_add_u32 s10, s10, 0x1000
	s_addc_u32 s11, s11, 0
	s_waitcnt vmcnt(53)
	v_sub_f32_e32 v84, v76, v80
	v_sub_f32_e32 v85, v77, v81
	v_sub_f32_e32 v86, v78, v82
	v_sub_f32_e32 v87, v79, v83
	v_pk_fma_f32 v[88:89], v[84:85], v[4:5], v[80:81]
	v_pk_fma_f32 v[90:91], v[86:87], v[6:7], v[82:83]
	v_pk_fma_f32 v[92:93], v[84:85], v[8:9], v[80:81]
	v_pk_fma_f32 v[94:95], v[86:87], v[10:11], v[82:83]
	v_pk_fma_f32 v[96:97], v[84:85], v[12:13], v[80:81]
	v_pk_fma_f32 v[98:99], v[86:87], v[14:15], v[82:83]
	v_cvt_pk_bf16_f32 v106, v88, v89
	v_cvt_pk_bf16_f32 v107, v90, v91
	v_cvt_pk_bf16_f32 v108, v92, v93
	v_cvt_pk_bf16_f32 v109, v94, v95
	v_cvt_pk_bf16_f32 v110, v96, v97
	v_cvt_pk_bf16_f32 v111, v98, v99
	global_store_dwordx2 v2, v[106:107], s[6:7]
	global_store_dwordx2 v2, v[108:109], s[8:9]
	global_store_dwordx2 v2, v[110:111], s[10:11]
	s_add_u32 s6, s6, 0x1000
	s_addc_u32 s7, s7, 0
	s_add_u32 s8, s8, 0x1000
	s_addc_u32 s9, s9, 0
	s_add_u32 s10, s10, 0x1000
	s_addc_u32 s11, s11, 0
	v_mov_b32_e32 v16, v80
	v_mov_b32_e32 v17, v81
	v_mov_b32_e32 v18, v82
	v_mov_b32_e32 v19, v83
	global_load_dwordx4 v[52:55], v1, s[4:5]
	s_add_u32 s4, s4, 0x2000
	s_addc_u32 s5, s5, 0
	global_load_dwordx4 v[56:59], v1, s[4:5]
	s_add_u32 s4, s4, 0x2000
	s_addc_u32 s5, s5, 0
	global_load_dwordx4 v[60:63], v1, s[4:5]
	s_add_u32 s4, s4, 0x2000
	s_addc_u32 s5, s5, 0
	global_load_dwordx4 v[64:67], v1, s[4:5]
	s_add_u32 s4, s4, 0x2000
	s_addc_u32 s5, s5, 0
	global_load_dwordx4 v[68:71], v1, s[4:5]
	s_add_u32 s4, s4, 0x2000
	s_addc_u32 s5, s5, 0
	global_load_dwordx4 v[72:75], v1, s[4:5]
	s_add_u32 s4, s4, 0x2000
	s_addc_u32 s5, s5, 0
	global_load_dwordx4 v[76:79], v1, s[4:5]
	s_add_u32 s4, s4, 0x2000
	s_addc_u32 s5, s5, 0
	global_load_dwordx4 v[80:83], v1, s[4:5]
	s_add_u32 s4, s4, 0x2000
	s_addc_u32 s5, s5, 0
	s_waitcnt vmcnt(39)
	v_sub_f32_e32 v84, v16, v20
	v_sub_f32_e32 v85, v17, v21
	v_sub_f32_e32 v86, v18, v22
	v_sub_f32_e32 v87, v19, v23
	v_pk_fma_f32 v[88:89], v[84:85], v[4:5], v[20:21]
	v_pk_fma_f32 v[90:91], v[86:87], v[6:7], v[22:23]
	v_pk_fma_f32 v[92:93], v[84:85], v[8:9], v[20:21]
	v_pk_fma_f32 v[94:95], v[86:87], v[10:11], v[22:23]
	v_pk_fma_f32 v[96:97], v[84:85], v[12:13], v[20:21]
	v_pk_fma_f32 v[98:99], v[86:87], v[14:15], v[22:23]
	v_cvt_pk_bf16_f32 v100, v88, v89
	v_cvt_pk_bf16_f32 v101, v90, v91
	v_cvt_pk_bf16_f32 v102, v92, v93
	v_cvt_pk_bf16_f32 v103, v94, v95
	v_cvt_pk_bf16_f32 v104, v96, v97
	v_cvt_pk_bf16_f32 v105, v98, v99
	global_store_dwordx2 v2, v[100:101], s[6:7]
	global_store_dwordx2 v2, v[102:103], s[8:9]
	global_store_dwordx2 v2, v[104:105], s[10:11]
	s_add_u32 s6, s6, 0x1000
	s_addc_u32 s7, s7, 0
	s_add_u32 s8, s8, 0x1000
	s_addc_u32 s9, s9, 0
	s_add_u32 s10, s10, 0x1000
	s_addc_u32 s11, s11, 0
	s_waitcnt vmcnt(41)
	v_sub_f32_e32 v84, v20, v24
	v_sub_f32_e32 v85, v21, v25
	v_sub_f32_e32 v86, v22, v26
	v_sub_f32_e32 v87, v23, v27
	v_pk_fma_f32 v[88:89], v[84:85], v[4:5], v[24:25]
	v_pk_fma_f32 v[90:91], v[86:87], v[6:7], v[26:27]
	v_pk_fma_f32 v[92:93], v[84:85], v[8:9], v[24:25]
	v_pk_fma_f32 v[94:95], v[86:87], v[10:11], v[26:27]
	v_pk_fma_f32 v[96:97], v[84:85], v[12:13], v[24:25]
	v_pk_fma_f32 v[98:99], v[86:87], v[14:15], v[26:27]
	v_cvt_pk_bf16_f32 v106, v88, v89
	v_cvt_pk_bf16_f32 v107, v90, v91
	v_cvt_pk_bf16_f32 v108, v92, v93
	v_cvt_pk_bf16_f32 v109, v94, v95
	v_cvt_pk_bf16_f32 v110, v96, v97
	v_cvt_pk_bf16_f32 v111, v98, v99
	global_store_dwordx2 v2, v[106:107], s[6:7]
	global_store_dwordx2 v2, v[108:109], s[8:9]
	global_store_dwordx2 v2, v[110:111], s[10:11]
	s_add_u32 s6, s6, 0x1000
	s_addc_u32 s7, s7, 0
	s_add_u32 s8, s8, 0x1000
	s_addc_u32 s9, s9, 0
	s_add_u32 s10, s10, 0x1000
	s_addc_u32 s11, s11, 0
	s_waitcnt vmcnt(43)
	v_sub_f32_e32 v84, v24, v28
	v_sub_f32_e32 v85, v25, v29
	v_sub_f32_e32 v86, v26, v30
	v_sub_f32_e32 v87, v27, v31
	v_pk_fma_f32 v[88:89], v[84:85], v[4:5], v[28:29]
	v_pk_fma_f32 v[90:91], v[86:87], v[6:7], v[30:31]
	v_pk_fma_f32 v[92:93], v[84:85], v[8:9], v[28:29]
	v_pk_fma_f32 v[94:95], v[86:87], v[10:11], v[30:31]
	v_pk_fma_f32 v[96:97], v[84:85], v[12:13], v[28:29]
	v_pk_fma_f32 v[98:99], v[86:87], v[14:15], v[30:31]
	v_cvt_pk_bf16_f32 v100, v88, v89
	v_cvt_pk_bf16_f32 v101, v90, v91
	v_cvt_pk_bf16_f32 v102, v92, v93
	v_cvt_pk_bf16_f32 v103, v94, v95
	v_cvt_pk_bf16_f32 v104, v96, v97
	v_cvt_pk_bf16_f32 v105, v98, v99
	global_store_dwordx2 v2, v[100:101], s[6:7]
	global_store_dwordx2 v2, v[102:103], s[8:9]
	global_store_dwordx2 v2, v[104:105], s[10:11]
	s_add_u32 s6, s6, 0x1000
	s_addc_u32 s7, s7, 0
	s_add_u32 s8, s8, 0x1000
	s_addc_u32 s9, s9, 0
	s_add_u32 s10, s10, 0x1000
	s_addc_u32 s11, s11, 0
	s_waitcnt vmcnt(45)
	v_sub_f32_e32 v84, v28, v32
	v_sub_f32_e32 v85, v29, v33
	v_sub_f32_e32 v86, v30, v34
	v_sub_f32_e32 v87, v31, v35
	v_pk_fma_f32 v[88:89], v[84:85], v[4:5], v[32:33]
	v_pk_fma_f32 v[90:91], v[86:87], v[6:7], v[34:35]
	v_pk_fma_f32 v[92:93], v[84:85], v[8:9], v[32:33]
	v_pk_fma_f32 v[94:95], v[86:87], v[10:11], v[34:35]
	v_pk_fma_f32 v[96:97], v[84:85], v[12:13], v[32:33]
	v_pk_fma_f32 v[98:99], v[86:87], v[14:15], v[34:35]
	v_cvt_pk_bf16_f32 v106, v88, v89
	v_cvt_pk_bf16_f32 v107, v90, v91
	v_cvt_pk_bf16_f32 v108, v92, v93
	v_cvt_pk_bf16_f32 v109, v94, v95
	v_cvt_pk_bf16_f32 v110, v96, v97
	v_cvt_pk_bf16_f32 v111, v98, v99
	global_store_dwordx2 v2, v[106:107], s[6:7]
	global_store_dwordx2 v2, v[108:109], s[8:9]
	global_store_dwordx2 v2, v[110:111], s[10:11]
	s_add_u32 s6, s6, 0x1000
	s_addc_u32 s7, s7, 0
	s_add_u32 s8, s8, 0x1000
	s_addc_u32 s9, s9, 0
	s_add_u32 s10, s10, 0x1000
	s_addc_u32 s11, s11, 0
	s_waitcnt vmcnt(47)
	v_sub_f32_e32 v84, v32, v36
	v_sub_f32_e32 v85, v33, v37
	v_sub_f32_e32 v86, v34, v38
	v_sub_f32_e32 v87, v35, v39
	v_pk_fma_f32 v[88:89], v[84:85], v[4:5], v[36:37]
	v_pk_fma_f32 v[90:91], v[86:87], v[6:7], v[38:39]
	v_pk_fma_f32 v[92:93], v[84:85], v[8:9], v[36:37]
	v_pk_fma_f32 v[94:95], v[86:87], v[10:11], v[38:39]
	v_pk_fma_f32 v[96:97], v[84:85], v[12:13], v[36:37]
	v_pk_fma_f32 v[98:99], v[86:87], v[14:15], v[38:39]
	v_cvt_pk_bf16_f32 v100, v88, v89
	v_cvt_pk_bf16_f32 v101, v90, v91
	v_cvt_pk_bf16_f32 v102, v92, v93
	v_cvt_pk_bf16_f32 v103, v94, v95
	v_cvt_pk_bf16_f32 v104, v96, v97
	v_cvt_pk_bf16_f32 v105, v98, v99
	global_store_dwordx2 v2, v[100:101], s[6:7]
	global_store_dwordx2 v2, v[102:103], s[8:9]
	global_store_dwordx2 v2, v[104:105], s[10:11]
	s_add_u32 s6, s6, 0x1000
	s_addc_u32 s7, s7, 0
	s_add_u32 s8, s8, 0x1000
	s_addc_u32 s9, s9, 0
	s_add_u32 s10, s10, 0x1000
	s_addc_u32 s11, s11, 0
	s_waitcnt vmcnt(49)
	v_sub_f32_e32 v84, v36, v40
	v_sub_f32_e32 v85, v37, v41
	v_sub_f32_e32 v86, v38, v42
	v_sub_f32_e32 v87, v39, v43
	v_pk_fma_f32 v[88:89], v[84:85], v[4:5], v[40:41]
	v_pk_fma_f32 v[90:91], v[86:87], v[6:7], v[42:43]
	v_pk_fma_f32 v[92:93], v[84:85], v[8:9], v[40:41]
	v_pk_fma_f32 v[94:95], v[86:87], v[10:11], v[42:43]
	v_pk_fma_f32 v[96:97], v[84:85], v[12:13], v[40:41]
	v_pk_fma_f32 v[98:99], v[86:87], v[14:15], v[42:43]
	v_cvt_pk_bf16_f32 v106, v88, v89
	v_cvt_pk_bf16_f32 v107, v90, v91
	v_cvt_pk_bf16_f32 v108, v92, v93
	v_cvt_pk_bf16_f32 v109, v94, v95
	v_cvt_pk_bf16_f32 v110, v96, v97
	v_cvt_pk_bf16_f32 v111, v98, v99
	global_store_dwordx2 v2, v[106:107], s[6:7]
	global_store_dwordx2 v2, v[108:109], s[8:9]
	global_store_dwordx2 v2, v[110:111], s[10:11]
	s_add_u32 s6, s6, 0x1000
	s_addc_u32 s7, s7, 0
	s_add_u32 s8, s8, 0x1000
	s_addc_u32 s9, s9, 0
	s_add_u32 s10, s10, 0x1000
	s_addc_u32 s11, s11, 0
	s_waitcnt vmcnt(51)
	v_sub_f32_e32 v84, v40, v44
	v_sub_f32_e32 v85, v41, v45
	v_sub_f32_e32 v86, v42, v46
	v_sub_f32_e32 v87, v43, v47
	v_pk_fma_f32 v[88:89], v[84:85], v[4:5], v[44:45]
	v_pk_fma_f32 v[90:91], v[86:87], v[6:7], v[46:47]
	v_pk_fma_f32 v[92:93], v[84:85], v[8:9], v[44:45]
	v_pk_fma_f32 v[94:95], v[86:87], v[10:11], v[46:47]
	v_pk_fma_f32 v[96:97], v[84:85], v[12:13], v[44:45]
	v_pk_fma_f32 v[98:99], v[86:87], v[14:15], v[46:47]
	v_cvt_pk_bf16_f32 v100, v88, v89
	v_cvt_pk_bf16_f32 v101, v90, v91
	v_cvt_pk_bf16_f32 v102, v92, v93
	v_cvt_pk_bf16_f32 v103, v94, v95
	v_cvt_pk_bf16_f32 v104, v96, v97
	v_cvt_pk_bf16_f32 v105, v98, v99
	global_store_dwordx2 v2, v[100:101], s[6:7]
	global_store_dwordx2 v2, v[102:103], s[8:9]
	global_store_dwordx2 v2, v[104:105], s[10:11]
	s_add_u32 s6, s6, 0x1000
	s_addc_u32 s7, s7, 0
	s_add_u32 s8, s8, 0x1000
	s_addc_u32 s9, s9, 0
	s_add_u32 s10, s10, 0x1000
	s_addc_u32 s11, s11, 0
	s_waitcnt vmcnt(53)
	v_sub_f32_e32 v84, v44, v48
	v_sub_f32_e32 v85, v45, v49
	v_sub_f32_e32 v86, v46, v50
	v_sub_f32_e32 v87, v47, v51
	v_pk_fma_f32 v[88:89], v[84:85], v[4:5], v[48:49]
	v_pk_fma_f32 v[90:91], v[86:87], v[6:7], v[50:51]
	v_pk_fma_f32 v[92:93], v[84:85], v[8:9], v[48:49]
	v_pk_fma_f32 v[94:95], v[86:87], v[10:11], v[50:51]
	v_pk_fma_f32 v[96:97], v[84:85], v[12:13], v[48:49]
	v_pk_fma_f32 v[98:99], v[86:87], v[14:15], v[50:51]
	v_cvt_pk_bf16_f32 v106, v88, v89
	v_cvt_pk_bf16_f32 v107, v90, v91
	v_cvt_pk_bf16_f32 v108, v92, v93
	v_cvt_pk_bf16_f32 v109, v94, v95
	v_cvt_pk_bf16_f32 v110, v96, v97
	v_cvt_pk_bf16_f32 v111, v98, v99
	global_store_dwordx2 v2, v[106:107], s[6:7]
	global_store_dwordx2 v2, v[108:109], s[8:9]
	global_store_dwordx2 v2, v[110:111], s[10:11]
	s_add_u32 s6, s6, 0x1000
	s_addc_u32 s7, s7, 0
	s_add_u32 s8, s8, 0x1000
	s_addc_u32 s9, s9, 0
	s_add_u32 s10, s10, 0x1000
	s_addc_u32 s11, s11, 0
	v_mov_b32_e32 v16, v48
	v_mov_b32_e32 v17, v49
	v_mov_b32_e32 v18, v50
	v_mov_b32_e32 v19, v51
	global_load_dwordx4 v[20:23], v1, s[4:5]
	s_add_u32 s4, s4, 0x2000
	s_addc_u32 s5, s5, 0
	global_load_dwordx4 v[24:27], v1, s[4:5]
	s_add_u32 s4, s4, 0x2000
	s_addc_u32 s5, s5, 0
	global_load_dwordx4 v[28:31], v1, s[4:5]
	s_add_u32 s4, s4, 0x2000
	s_addc_u32 s5, s5, 0
	global_load_dwordx4 v[32:35], v1, s[4:5]
	s_add_u32 s4, s4, 0x2000
	s_addc_u32 s5, s5, 0
	global_load_dwordx4 v[36:39], v1, s[4:5]
	s_add_u32 s4, s4, 0x2000
	s_addc_u32 s5, s5, 0
	global_load_dwordx4 v[40:43], v1, s[4:5]
	s_add_u32 s4, s4, 0x2000
	s_addc_u32 s5, s5, 0
	global_load_dwordx4 v[44:47], v1, s[4:5]
	s_add_u32 s4, s4, 0x2000
	s_addc_u32 s5, s5, 0
	global_load_dwordx4 v[48:51], v1, s[4:5]
	s_add_u32 s4, s4, 0x2000
	s_addc_u32 s5, s5, 0
	s_waitcnt vmcnt(39)
	v_sub_f32_e32 v84, v16, v52
	v_sub_f32_e32 v85, v17, v53
	v_sub_f32_e32 v86, v18, v54
	v_sub_f32_e32 v87, v19, v55
	v_pk_fma_f32 v[88:89], v[84:85], v[4:5], v[52:53]
	v_pk_fma_f32 v[90:91], v[86:87], v[6:7], v[54:55]
	v_pk_fma_f32 v[92:93], v[84:85], v[8:9], v[52:53]
	v_pk_fma_f32 v[94:95], v[86:87], v[10:11], v[54:55]
	v_pk_fma_f32 v[96:97], v[84:85], v[12:13], v[52:53]
	v_pk_fma_f32 v[98:99], v[86:87], v[14:15], v[54:55]
	v_cvt_pk_bf16_f32 v100, v88, v89
	v_cvt_pk_bf16_f32 v101, v90, v91
	v_cvt_pk_bf16_f32 v102, v92, v93
	v_cvt_pk_bf16_f32 v103, v94, v95
	v_cvt_pk_bf16_f32 v104, v96, v97
	v_cvt_pk_bf16_f32 v105, v98, v99
	global_store_dwordx2 v2, v[100:101], s[6:7]
	global_store_dwordx2 v2, v[102:103], s[8:9]
	global_store_dwordx2 v2, v[104:105], s[10:11]
	s_add_u32 s6, s6, 0x1000
	s_addc_u32 s7, s7, 0
	s_add_u32 s8, s8, 0x1000
	s_addc_u32 s9, s9, 0
	s_add_u32 s10, s10, 0x1000
	s_addc_u32 s11, s11, 0
	s_waitcnt vmcnt(41)
	v_sub_f32_e32 v84, v52, v56
	v_sub_f32_e32 v85, v53, v57
	v_sub_f32_e32 v86, v54, v58
	v_sub_f32_e32 v87, v55, v59
	v_pk_fma_f32 v[88:89], v[84:85], v[4:5], v[56:57]
	v_pk_fma_f32 v[90:91], v[86:87], v[6:7], v[58:59]
	v_pk_fma_f32 v[92:93], v[84:85], v[8:9], v[56:57]
	v_pk_fma_f32 v[94:95], v[86:87], v[10:11], v[58:59]
	v_pk_fma_f32 v[96:97], v[84:85], v[12:13], v[56:57]
	v_pk_fma_f32 v[98:99], v[86:87], v[14:15], v[58:59]
	v_cvt_pk_bf16_f32 v106, v88, v89
	v_cvt_pk_bf16_f32 v107, v90, v91
	v_cvt_pk_bf16_f32 v108, v92, v93
	v_cvt_pk_bf16_f32 v109, v94, v95
	v_cvt_pk_bf16_f32 v110, v96, v97
	v_cvt_pk_bf16_f32 v111, v98, v99
	global_store_dwordx2 v2, v[106:107], s[6:7]
	global_store_dwordx2 v2, v[108:109], s[8:9]
	global_store_dwordx2 v2, v[110:111], s[10:11]
	s_add_u32 s6, s6, 0x1000
	s_addc_u32 s7, s7, 0
	s_add_u32 s8, s8, 0x1000
	s_addc_u32 s9, s9, 0
	s_add_u32 s10, s10, 0x1000
	s_addc_u32 s11, s11, 0
	s_waitcnt vmcnt(43)
	v_sub_f32_e32 v84, v56, v60
	v_sub_f32_e32 v85, v57, v61
	v_sub_f32_e32 v86, v58, v62
	v_sub_f32_e32 v87, v59, v63
	v_pk_fma_f32 v[88:89], v[84:85], v[4:5], v[60:61]
	v_pk_fma_f32 v[90:91], v[86:87], v[6:7], v[62:63]
	v_pk_fma_f32 v[92:93], v[84:85], v[8:9], v[60:61]
	v_pk_fma_f32 v[94:95], v[86:87], v[10:11], v[62:63]
	v_pk_fma_f32 v[96:97], v[84:85], v[12:13], v[60:61]
	v_pk_fma_f32 v[98:99], v[86:87], v[14:15], v[62:63]
	v_cvt_pk_bf16_f32 v100, v88, v89
	v_cvt_pk_bf16_f32 v101, v90, v91
	v_cvt_pk_bf16_f32 v102, v92, v93
	v_cvt_pk_bf16_f32 v103, v94, v95
	v_cvt_pk_bf16_f32 v104, v96, v97
	v_cvt_pk_bf16_f32 v105, v98, v99
	global_store_dwordx2 v2, v[100:101], s[6:7]
	global_store_dwordx2 v2, v[102:103], s[8:9]
	global_store_dwordx2 v2, v[104:105], s[10:11]
	s_add_u32 s6, s6, 0x1000
	s_addc_u32 s7, s7, 0
	s_add_u32 s8, s8, 0x1000
	s_addc_u32 s9, s9, 0
	s_add_u32 s10, s10, 0x1000
	s_addc_u32 s11, s11, 0
	s_waitcnt vmcnt(45)
	v_sub_f32_e32 v84, v60, v64
	v_sub_f32_e32 v85, v61, v65
	v_sub_f32_e32 v86, v62, v66
	v_sub_f32_e32 v87, v63, v67
	v_pk_fma_f32 v[88:89], v[84:85], v[4:5], v[64:65]
	v_pk_fma_f32 v[90:91], v[86:87], v[6:7], v[66:67]
	v_pk_fma_f32 v[92:93], v[84:85], v[8:9], v[64:65]
	v_pk_fma_f32 v[94:95], v[86:87], v[10:11], v[66:67]
	v_pk_fma_f32 v[96:97], v[84:85], v[12:13], v[64:65]
	v_pk_fma_f32 v[98:99], v[86:87], v[14:15], v[66:67]
	v_cvt_pk_bf16_f32 v106, v88, v89
	v_cvt_pk_bf16_f32 v107, v90, v91
	v_cvt_pk_bf16_f32 v108, v92, v93
	v_cvt_pk_bf16_f32 v109, v94, v95
	v_cvt_pk_bf16_f32 v110, v96, v97
	v_cvt_pk_bf16_f32 v111, v98, v99
	global_store_dwordx2 v2, v[106:107], s[6:7]
	global_store_dwordx2 v2, v[108:109], s[8:9]
	global_store_dwordx2 v2, v[110:111], s[10:11]
	s_add_u32 s6, s6, 0x1000
	s_addc_u32 s7, s7, 0
	s_add_u32 s8, s8, 0x1000
	s_addc_u32 s9, s9, 0
	s_add_u32 s10, s10, 0x1000
	s_addc_u32 s11, s11, 0
	s_waitcnt vmcnt(47)
	v_sub_f32_e32 v84, v64, v68
	v_sub_f32_e32 v85, v65, v69
	v_sub_f32_e32 v86, v66, v70
	v_sub_f32_e32 v87, v67, v71
	v_pk_fma_f32 v[88:89], v[84:85], v[4:5], v[68:69]
	v_pk_fma_f32 v[90:91], v[86:87], v[6:7], v[70:71]
	v_pk_fma_f32 v[92:93], v[84:85], v[8:9], v[68:69]
	v_pk_fma_f32 v[94:95], v[86:87], v[10:11], v[70:71]
	v_pk_fma_f32 v[96:97], v[84:85], v[12:13], v[68:69]
	v_pk_fma_f32 v[98:99], v[86:87], v[14:15], v[70:71]
	v_cvt_pk_bf16_f32 v100, v88, v89
	v_cvt_pk_bf16_f32 v101, v90, v91
	v_cvt_pk_bf16_f32 v102, v92, v93
	v_cvt_pk_bf16_f32 v103, v94, v95
	v_cvt_pk_bf16_f32 v104, v96, v97
	v_cvt_pk_bf16_f32 v105, v98, v99
	global_store_dwordx2 v2, v[100:101], s[6:7]
	global_store_dwordx2 v2, v[102:103], s[8:9]
	global_store_dwordx2 v2, v[104:105], s[10:11]
	s_add_u32 s6, s6, 0x1000
	s_addc_u32 s7, s7, 0
	s_add_u32 s8, s8, 0x1000
	s_addc_u32 s9, s9, 0
	s_add_u32 s10, s10, 0x1000
	s_addc_u32 s11, s11, 0
	s_waitcnt vmcnt(49)
	v_sub_f32_e32 v84, v68, v72
	v_sub_f32_e32 v85, v69, v73
	v_sub_f32_e32 v86, v70, v74
	v_sub_f32_e32 v87, v71, v75
	v_pk_fma_f32 v[88:89], v[84:85], v[4:5], v[72:73]
	v_pk_fma_f32 v[90:91], v[86:87], v[6:7], v[74:75]
	v_pk_fma_f32 v[92:93], v[84:85], v[8:9], v[72:73]
	v_pk_fma_f32 v[94:95], v[86:87], v[10:11], v[74:75]
	v_pk_fma_f32 v[96:97], v[84:85], v[12:13], v[72:73]
	v_pk_fma_f32 v[98:99], v[86:87], v[14:15], v[74:75]
	v_cvt_pk_bf16_f32 v106, v88, v89
	v_cvt_pk_bf16_f32 v107, v90, v91
	v_cvt_pk_bf16_f32 v108, v92, v93
	v_cvt_pk_bf16_f32 v109, v94, v95
	v_cvt_pk_bf16_f32 v110, v96, v97
	v_cvt_pk_bf16_f32 v111, v98, v99
	global_store_dwordx2 v2, v[106:107], s[6:7]
	global_store_dwordx2 v2, v[108:109], s[8:9]
	global_store_dwordx2 v2, v[110:111], s[10:11]
	s_add_u32 s6, s6, 0x1000
	s_addc_u32 s7, s7, 0
	s_add_u32 s8, s8, 0x1000
	s_addc_u32 s9, s9, 0
	s_add_u32 s10, s10, 0x1000
	s_addc_u32 s11, s11, 0
	s_waitcnt vmcnt(51)
	v_sub_f32_e32 v84, v72, v76
	v_sub_f32_e32 v85, v73, v77
	v_sub_f32_e32 v86, v74, v78
	v_sub_f32_e32 v87, v75, v79
	v_pk_fma_f32 v[88:89], v[84:85], v[4:5], v[76:77]
	v_pk_fma_f32 v[90:91], v[86:87], v[6:7], v[78:79]
	v_pk_fma_f32 v[92:93], v[84:85], v[8:9], v[76:77]
	v_pk_fma_f32 v[94:95], v[86:87], v[10:11], v[78:79]
	v_pk_fma_f32 v[96:97], v[84:85], v[12:13], v[76:77]
	v_pk_fma_f32 v[98:99], v[86:87], v[14:15], v[78:79]
	v_cvt_pk_bf16_f32 v100, v88, v89
	v_cvt_pk_bf16_f32 v101, v90, v91
	v_cvt_pk_bf16_f32 v102, v92, v93
	v_cvt_pk_bf16_f32 v103, v94, v95
	v_cvt_pk_bf16_f32 v104, v96, v97
	v_cvt_pk_bf16_f32 v105, v98, v99
	global_store_dwordx2 v2, v[100:101], s[6:7]
	global_store_dwordx2 v2, v[102:103], s[8:9]
	global_store_dwordx2 v2, v[104:105], s[10:11]
	s_add_u32 s6, s6, 0x1000
	s_addc_u32 s7, s7, 0
	s_add_u32 s8, s8, 0x1000
	s_addc_u32 s9, s9, 0
	s_add_u32 s10, s10, 0x1000
	s_addc_u32 s11, s11, 0
	s_waitcnt vmcnt(53)
	v_sub_f32_e32 v84, v76, v80
	v_sub_f32_e32 v85, v77, v81
	v_sub_f32_e32 v86, v78, v82
	v_sub_f32_e32 v87, v79, v83
	v_pk_fma_f32 v[88:89], v[84:85], v[4:5], v[80:81]
	v_pk_fma_f32 v[90:91], v[86:87], v[6:7], v[82:83]
	v_pk_fma_f32 v[92:93], v[84:85], v[8:9], v[80:81]
	v_pk_fma_f32 v[94:95], v[86:87], v[10:11], v[82:83]
	v_pk_fma_f32 v[96:97], v[84:85], v[12:13], v[80:81]
	v_pk_fma_f32 v[98:99], v[86:87], v[14:15], v[82:83]
	v_cvt_pk_bf16_f32 v106, v88, v89
	v_cvt_pk_bf16_f32 v107, v90, v91
	v_cvt_pk_bf16_f32 v108, v92, v93
	v_cvt_pk_bf16_f32 v109, v94, v95
	v_cvt_pk_bf16_f32 v110, v96, v97
	v_cvt_pk_bf16_f32 v111, v98, v99
	global_store_dwordx2 v2, v[106:107], s[6:7]
	global_store_dwordx2 v2, v[108:109], s[8:9]
	global_store_dwordx2 v2, v[110:111], s[10:11]
	s_add_u32 s6, s6, 0x1000
	s_addc_u32 s7, s7, 0
	s_add_u32 s8, s8, 0x1000
	s_addc_u32 s9, s9, 0
	s_add_u32 s10, s10, 0x1000
	s_addc_u32 s11, s11, 0
	v_mov_b32_e32 v16, v80
	v_mov_b32_e32 v17, v81
	v_mov_b32_e32 v18, v82
	v_mov_b32_e32 v19, v83
	global_load_dwordx4 v[52:55], v1, s[4:5]
	s_add_u32 s4, s4, 0x2000
	s_addc_u32 s5, s5, 0
	global_load_dwordx4 v[56:59], v1, s[4:5]
	s_add_u32 s4, s4, 0x2000
	s_addc_u32 s5, s5, 0
	global_load_dwordx4 v[60:63], v1, s[4:5]
	s_add_u32 s4, s4, 0x2000
	s_addc_u32 s5, s5, 0
	global_load_dwordx4 v[64:67], v1, s[4:5]
	s_add_u32 s4, s4, 0x2000
	s_addc_u32 s5, s5, 0
	global_load_dwordx4 v[68:71], v1, s[4:5]
	s_add_u32 s4, s4, 0x2000
	s_addc_u32 s5, s5, 0
	global_load_dwordx4 v[72:75], v1, s[4:5]
	s_add_u32 s4, s4, 0x2000
	s_addc_u32 s5, s5, 0
	global_load_dwordx4 v[76:79], v1, s[4:5]
	s_add_u32 s4, s4, 0x2000
	s_addc_u32 s5, s5, 0
	global_load_dwordx4 v[80:83], v1, s[4:5]
	s_add_u32 s4, s4, 0x2000
	s_addc_u32 s5, s5, 0
	s_waitcnt vmcnt(39)
	v_sub_f32_e32 v84, v16, v20
	v_sub_f32_e32 v85, v17, v21
	v_sub_f32_e32 v86, v18, v22
	v_sub_f32_e32 v87, v19, v23
	v_pk_fma_f32 v[88:89], v[84:85], v[4:5], v[20:21]
	v_pk_fma_f32 v[90:91], v[86:87], v[6:7], v[22:23]
	v_pk_fma_f32 v[92:93], v[84:85], v[8:9], v[20:21]
	v_pk_fma_f32 v[94:95], v[86:87], v[10:11], v[22:23]
	v_pk_fma_f32 v[96:97], v[84:85], v[12:13], v[20:21]
	v_pk_fma_f32 v[98:99], v[86:87], v[14:15], v[22:23]
	v_cvt_pk_bf16_f32 v100, v88, v89
	v_cvt_pk_bf16_f32 v101, v90, v91
	v_cvt_pk_bf16_f32 v102, v92, v93
	v_cvt_pk_bf16_f32 v103, v94, v95
	v_cvt_pk_bf16_f32 v104, v96, v97
	v_cvt_pk_bf16_f32 v105, v98, v99
	global_store_dwordx2 v2, v[100:101], s[6:7]
	global_store_dwordx2 v2, v[102:103], s[8:9]
	global_store_dwordx2 v2, v[104:105], s[10:11]
	s_add_u32 s6, s6, 0x1000
	s_addc_u32 s7, s7, 0
	s_add_u32 s8, s8, 0x1000
	s_addc_u32 s9, s9, 0
	s_add_u32 s10, s10, 0x1000
	s_addc_u32 s11, s11, 0
	s_waitcnt vmcnt(41)
	v_sub_f32_e32 v84, v20, v24
	v_sub_f32_e32 v85, v21, v25
	v_sub_f32_e32 v86, v22, v26
	v_sub_f32_e32 v87, v23, v27
	v_pk_fma_f32 v[88:89], v[84:85], v[4:5], v[24:25]
	v_pk_fma_f32 v[90:91], v[86:87], v[6:7], v[26:27]
	v_pk_fma_f32 v[92:93], v[84:85], v[8:9], v[24:25]
	v_pk_fma_f32 v[94:95], v[86:87], v[10:11], v[26:27]
	v_pk_fma_f32 v[96:97], v[84:85], v[12:13], v[24:25]
	v_pk_fma_f32 v[98:99], v[86:87], v[14:15], v[26:27]
	v_cvt_pk_bf16_f32 v106, v88, v89
	v_cvt_pk_bf16_f32 v107, v90, v91
	v_cvt_pk_bf16_f32 v108, v92, v93
	v_cvt_pk_bf16_f32 v109, v94, v95
	v_cvt_pk_bf16_f32 v110, v96, v97
	v_cvt_pk_bf16_f32 v111, v98, v99
	global_store_dwordx2 v2, v[106:107], s[6:7]
	global_store_dwordx2 v2, v[108:109], s[8:9]
	global_store_dwordx2 v2, v[110:111], s[10:11]
	s_add_u32 s6, s6, 0x1000
	s_addc_u32 s7, s7, 0
	s_add_u32 s8, s8, 0x1000
	s_addc_u32 s9, s9, 0
	s_add_u32 s10, s10, 0x1000
	s_addc_u32 s11, s11, 0
	s_waitcnt vmcnt(43)
	v_sub_f32_e32 v84, v24, v28
	v_sub_f32_e32 v85, v25, v29
	v_sub_f32_e32 v86, v26, v30
	v_sub_f32_e32 v87, v27, v31
	v_pk_fma_f32 v[88:89], v[84:85], v[4:5], v[28:29]
	v_pk_fma_f32 v[90:91], v[86:87], v[6:7], v[30:31]
	v_pk_fma_f32 v[92:93], v[84:85], v[8:9], v[28:29]
	v_pk_fma_f32 v[94:95], v[86:87], v[10:11], v[30:31]
	v_pk_fma_f32 v[96:97], v[84:85], v[12:13], v[28:29]
	v_pk_fma_f32 v[98:99], v[86:87], v[14:15], v[30:31]
	v_cvt_pk_bf16_f32 v100, v88, v89
	v_cvt_pk_bf16_f32 v101, v90, v91
	v_cvt_pk_bf16_f32 v102, v92, v93
	v_cvt_pk_bf16_f32 v103, v94, v95
	v_cvt_pk_bf16_f32 v104, v96, v97
	v_cvt_pk_bf16_f32 v105, v98, v99
	global_store_dwordx2 v2, v[100:101], s[6:7]
	global_store_dwordx2 v2, v[102:103], s[8:9]
	global_store_dwordx2 v2, v[104:105], s[10:11]
	s_add_u32 s6, s6, 0x1000
	s_addc_u32 s7, s7, 0
	s_add_u32 s8, s8, 0x1000
	s_addc_u32 s9, s9, 0
	s_add_u32 s10, s10, 0x1000
	s_addc_u32 s11, s11, 0
	s_waitcnt vmcnt(45)
	v_sub_f32_e32 v84, v28, v32
	v_sub_f32_e32 v85, v29, v33
	v_sub_f32_e32 v86, v30, v34
	v_sub_f32_e32 v87, v31, v35
	v_pk_fma_f32 v[88:89], v[84:85], v[4:5], v[32:33]
	v_pk_fma_f32 v[90:91], v[86:87], v[6:7], v[34:35]
	v_pk_fma_f32 v[92:93], v[84:85], v[8:9], v[32:33]
	v_pk_fma_f32 v[94:95], v[86:87], v[10:11], v[34:35]
	v_pk_fma_f32 v[96:97], v[84:85], v[12:13], v[32:33]
	v_pk_fma_f32 v[98:99], v[86:87], v[14:15], v[34:35]
	v_cvt_pk_bf16_f32 v106, v88, v89
	v_cvt_pk_bf16_f32 v107, v90, v91
	v_cvt_pk_bf16_f32 v108, v92, v93
	v_cvt_pk_bf16_f32 v109, v94, v95
	v_cvt_pk_bf16_f32 v110, v96, v97
	v_cvt_pk_bf16_f32 v111, v98, v99
	global_store_dwordx2 v2, v[106:107], s[6:7]
	global_store_dwordx2 v2, v[108:109], s[8:9]
	global_store_dwordx2 v2, v[110:111], s[10:11]
	s_add_u32 s6, s6, 0x1000
	s_addc_u32 s7, s7, 0
	s_add_u32 s8, s8, 0x1000
	s_addc_u32 s9, s9, 0
	s_add_u32 s10, s10, 0x1000
	s_addc_u32 s11, s11, 0
	s_waitcnt vmcnt(47)
	v_sub_f32_e32 v84, v32, v36
	v_sub_f32_e32 v85, v33, v37
	v_sub_f32_e32 v86, v34, v38
	v_sub_f32_e32 v87, v35, v39
	v_pk_fma_f32 v[88:89], v[84:85], v[4:5], v[36:37]
	v_pk_fma_f32 v[90:91], v[86:87], v[6:7], v[38:39]
	v_pk_fma_f32 v[92:93], v[84:85], v[8:9], v[36:37]
	v_pk_fma_f32 v[94:95], v[86:87], v[10:11], v[38:39]
	v_pk_fma_f32 v[96:97], v[84:85], v[12:13], v[36:37]
	v_pk_fma_f32 v[98:99], v[86:87], v[14:15], v[38:39]
	v_cvt_pk_bf16_f32 v100, v88, v89
	v_cvt_pk_bf16_f32 v101, v90, v91
	v_cvt_pk_bf16_f32 v102, v92, v93
	v_cvt_pk_bf16_f32 v103, v94, v95
	v_cvt_pk_bf16_f32 v104, v96, v97
	v_cvt_pk_bf16_f32 v105, v98, v99
	global_store_dwordx2 v2, v[100:101], s[6:7]
	global_store_dwordx2 v2, v[102:103], s[8:9]
	global_store_dwordx2 v2, v[104:105], s[10:11]
	s_add_u32 s6, s6, 0x1000
	s_addc_u32 s7, s7, 0
	s_add_u32 s8, s8, 0x1000
	s_addc_u32 s9, s9, 0
	s_add_u32 s10, s10, 0x1000
	s_addc_u32 s11, s11, 0
	s_waitcnt vmcnt(49)
	v_sub_f32_e32 v84, v36, v40
	v_sub_f32_e32 v85, v37, v41
	v_sub_f32_e32 v86, v38, v42
	v_sub_f32_e32 v87, v39, v43
	v_pk_fma_f32 v[88:89], v[84:85], v[4:5], v[40:41]
	v_pk_fma_f32 v[90:91], v[86:87], v[6:7], v[42:43]
	v_pk_fma_f32 v[92:93], v[84:85], v[8:9], v[40:41]
	v_pk_fma_f32 v[94:95], v[86:87], v[10:11], v[42:43]
	v_pk_fma_f32 v[96:97], v[84:85], v[12:13], v[40:41]
	v_pk_fma_f32 v[98:99], v[86:87], v[14:15], v[42:43]
	v_cvt_pk_bf16_f32 v106, v88, v89
	v_cvt_pk_bf16_f32 v107, v90, v91
	v_cvt_pk_bf16_f32 v108, v92, v93
	v_cvt_pk_bf16_f32 v109, v94, v95
	v_cvt_pk_bf16_f32 v110, v96, v97
	v_cvt_pk_bf16_f32 v111, v98, v99
	global_store_dwordx2 v2, v[106:107], s[6:7]
	global_store_dwordx2 v2, v[108:109], s[8:9]
	global_store_dwordx2 v2, v[110:111], s[10:11]
	s_add_u32 s6, s6, 0x1000
	s_addc_u32 s7, s7, 0
	s_add_u32 s8, s8, 0x1000
	s_addc_u32 s9, s9, 0
	s_add_u32 s10, s10, 0x1000
	s_addc_u32 s11, s11, 0
	s_waitcnt vmcnt(51)
	v_sub_f32_e32 v84, v40, v44
	v_sub_f32_e32 v85, v41, v45
	v_sub_f32_e32 v86, v42, v46
	v_sub_f32_e32 v87, v43, v47
	v_pk_fma_f32 v[88:89], v[84:85], v[4:5], v[44:45]
	v_pk_fma_f32 v[90:91], v[86:87], v[6:7], v[46:47]
	v_pk_fma_f32 v[92:93], v[84:85], v[8:9], v[44:45]
	v_pk_fma_f32 v[94:95], v[86:87], v[10:11], v[46:47]
	v_pk_fma_f32 v[96:97], v[84:85], v[12:13], v[44:45]
	v_pk_fma_f32 v[98:99], v[86:87], v[14:15], v[46:47]
	v_cvt_pk_bf16_f32 v100, v88, v89
	v_cvt_pk_bf16_f32 v101, v90, v91
	v_cvt_pk_bf16_f32 v102, v92, v93
	v_cvt_pk_bf16_f32 v103, v94, v95
	v_cvt_pk_bf16_f32 v104, v96, v97
	v_cvt_pk_bf16_f32 v105, v98, v99
	global_store_dwordx2 v2, v[100:101], s[6:7]
	global_store_dwordx2 v2, v[102:103], s[8:9]
	global_store_dwordx2 v2, v[104:105], s[10:11]
	s_add_u32 s6, s6, 0x1000
	s_addc_u32 s7, s7, 0
	s_add_u32 s8, s8, 0x1000
	s_addc_u32 s9, s9, 0
	s_add_u32 s10, s10, 0x1000
	s_addc_u32 s11, s11, 0
	s_waitcnt vmcnt(53)
	v_sub_f32_e32 v84, v44, v48
	v_sub_f32_e32 v85, v45, v49
	v_sub_f32_e32 v86, v46, v50
	v_sub_f32_e32 v87, v47, v51
	v_pk_fma_f32 v[88:89], v[84:85], v[4:5], v[48:49]
	v_pk_fma_f32 v[90:91], v[86:87], v[6:7], v[50:51]
	v_pk_fma_f32 v[92:93], v[84:85], v[8:9], v[48:49]
	v_pk_fma_f32 v[94:95], v[86:87], v[10:11], v[50:51]
	v_pk_fma_f32 v[96:97], v[84:85], v[12:13], v[48:49]
	v_pk_fma_f32 v[98:99], v[86:87], v[14:15], v[50:51]
	v_cvt_pk_bf16_f32 v106, v88, v89
	v_cvt_pk_bf16_f32 v107, v90, v91
	v_cvt_pk_bf16_f32 v108, v92, v93
	v_cvt_pk_bf16_f32 v109, v94, v95
	v_cvt_pk_bf16_f32 v110, v96, v97
	v_cvt_pk_bf16_f32 v111, v98, v99
	global_store_dwordx2 v2, v[106:107], s[6:7]
	global_store_dwordx2 v2, v[108:109], s[8:9]
	global_store_dwordx2 v2, v[110:111], s[10:11]
	s_add_u32 s6, s6, 0x1000
	s_addc_u32 s7, s7, 0
	s_add_u32 s8, s8, 0x1000
	s_addc_u32 s9, s9, 0
	s_add_u32 s10, s10, 0x1000
	s_addc_u32 s11, s11, 0
	v_mov_b32_e32 v16, v48
	v_mov_b32_e32 v17, v49
	v_mov_b32_e32 v18, v50
	v_mov_b32_e32 v19, v51
	global_load_dwordx4 v[20:23], v1, s[4:5]
	s_add_u32 s4, s4, 0x2000
	s_addc_u32 s5, s5, 0
	global_load_dwordx4 v[24:27], v1, s[4:5]
	s_add_u32 s4, s4, 0x2000
	s_addc_u32 s5, s5, 0
	global_load_dwordx4 v[28:31], v1, s[4:5]
	s_add_u32 s4, s4, 0x2000
	s_addc_u32 s5, s5, 0
	global_load_dwordx4 v[32:35], v1, s[4:5]
	s_add_u32 s4, s4, 0x2000
	s_addc_u32 s5, s5, 0
	global_load_dwordx4 v[36:39], v1, s[4:5]
	s_add_u32 s4, s4, 0x2000
	s_addc_u32 s5, s5, 0
	global_load_dwordx4 v[40:43], v1, s[4:5]
	s_add_u32 s4, s4, 0x2000
	s_addc_u32 s5, s5, 0
	global_load_dwordx4 v[44:47], v1, s[4:5]
	s_add_u32 s4, s4, 0x2000
	s_addc_u32 s5, s5, 0
	global_load_dwordx4 v[48:51], v1, s[4:5]
	s_add_u32 s4, s4, 0x2000
	s_addc_u32 s5, s5, 0
	s_waitcnt vmcnt(39)
	v_sub_f32_e32 v84, v16, v52
	v_sub_f32_e32 v85, v17, v53
	v_sub_f32_e32 v86, v18, v54
	v_sub_f32_e32 v87, v19, v55
	v_pk_fma_f32 v[88:89], v[84:85], v[4:5], v[52:53]
	v_pk_fma_f32 v[90:91], v[86:87], v[6:7], v[54:55]
	v_pk_fma_f32 v[92:93], v[84:85], v[8:9], v[52:53]
	v_pk_fma_f32 v[94:95], v[86:87], v[10:11], v[54:55]
	v_pk_fma_f32 v[96:97], v[84:85], v[12:13], v[52:53]
	v_pk_fma_f32 v[98:99], v[86:87], v[14:15], v[54:55]
	v_cvt_pk_bf16_f32 v100, v88, v89
	v_cvt_pk_bf16_f32 v101, v90, v91
	v_cvt_pk_bf16_f32 v102, v92, v93
	v_cvt_pk_bf16_f32 v103, v94, v95
	v_cvt_pk_bf16_f32 v104, v96, v97
	v_cvt_pk_bf16_f32 v105, v98, v99
	global_store_dwordx2 v2, v[100:101], s[6:7]
	global_store_dwordx2 v2, v[102:103], s[8:9]
	global_store_dwordx2 v2, v[104:105], s[10:11]
	s_add_u32 s6, s6, 0x1000
	s_addc_u32 s7, s7, 0
	s_add_u32 s8, s8, 0x1000
	s_addc_u32 s9, s9, 0
	s_add_u32 s10, s10, 0x1000
	s_addc_u32 s11, s11, 0
	s_waitcnt vmcnt(41)
	v_sub_f32_e32 v84, v52, v56
	v_sub_f32_e32 v85, v53, v57
	v_sub_f32_e32 v86, v54, v58
	v_sub_f32_e32 v87, v55, v59
	v_pk_fma_f32 v[88:89], v[84:85], v[4:5], v[56:57]
	v_pk_fma_f32 v[90:91], v[86:87], v[6:7], v[58:59]
	v_pk_fma_f32 v[92:93], v[84:85], v[8:9], v[56:57]
	v_pk_fma_f32 v[94:95], v[86:87], v[10:11], v[58:59]
	v_pk_fma_f32 v[96:97], v[84:85], v[12:13], v[56:57]
	v_pk_fma_f32 v[98:99], v[86:87], v[14:15], v[58:59]
	v_cvt_pk_bf16_f32 v106, v88, v89
	v_cvt_pk_bf16_f32 v107, v90, v91
	v_cvt_pk_bf16_f32 v108, v92, v93
	v_cvt_pk_bf16_f32 v109, v94, v95
	v_cvt_pk_bf16_f32 v110, v96, v97
	v_cvt_pk_bf16_f32 v111, v98, v99
	global_store_dwordx2 v2, v[106:107], s[6:7]
	global_store_dwordx2 v2, v[108:109], s[8:9]
	global_store_dwordx2 v2, v[110:111], s[10:11]
	s_add_u32 s6, s6, 0x1000
	s_addc_u32 s7, s7, 0
	s_add_u32 s8, s8, 0x1000
	s_addc_u32 s9, s9, 0
	s_add_u32 s10, s10, 0x1000
	s_addc_u32 s11, s11, 0
	s_waitcnt vmcnt(43)
	v_sub_f32_e32 v84, v56, v60
	v_sub_f32_e32 v85, v57, v61
	v_sub_f32_e32 v86, v58, v62
	v_sub_f32_e32 v87, v59, v63
	v_pk_fma_f32 v[88:89], v[84:85], v[4:5], v[60:61]
	v_pk_fma_f32 v[90:91], v[86:87], v[6:7], v[62:63]
	v_pk_fma_f32 v[92:93], v[84:85], v[8:9], v[60:61]
	v_pk_fma_f32 v[94:95], v[86:87], v[10:11], v[62:63]
	v_pk_fma_f32 v[96:97], v[84:85], v[12:13], v[60:61]
	v_pk_fma_f32 v[98:99], v[86:87], v[14:15], v[62:63]
	v_cvt_pk_bf16_f32 v100, v88, v89
	v_cvt_pk_bf16_f32 v101, v90, v91
	v_cvt_pk_bf16_f32 v102, v92, v93
	v_cvt_pk_bf16_f32 v103, v94, v95
	v_cvt_pk_bf16_f32 v104, v96, v97
	v_cvt_pk_bf16_f32 v105, v98, v99
	global_store_dwordx2 v2, v[100:101], s[6:7]
	global_store_dwordx2 v2, v[102:103], s[8:9]
	global_store_dwordx2 v2, v[104:105], s[10:11]
	s_add_u32 s6, s6, 0x1000
	s_addc_u32 s7, s7, 0
	s_add_u32 s8, s8, 0x1000
	s_addc_u32 s9, s9, 0
	s_add_u32 s10, s10, 0x1000
	s_addc_u32 s11, s11, 0
	s_waitcnt vmcnt(45)
	v_sub_f32_e32 v84, v60, v64
	v_sub_f32_e32 v85, v61, v65
	v_sub_f32_e32 v86, v62, v66
	v_sub_f32_e32 v87, v63, v67
	v_pk_fma_f32 v[88:89], v[84:85], v[4:5], v[64:65]
	v_pk_fma_f32 v[90:91], v[86:87], v[6:7], v[66:67]
	v_pk_fma_f32 v[92:93], v[84:85], v[8:9], v[64:65]
	v_pk_fma_f32 v[94:95], v[86:87], v[10:11], v[66:67]
	v_pk_fma_f32 v[96:97], v[84:85], v[12:13], v[64:65]
	v_pk_fma_f32 v[98:99], v[86:87], v[14:15], v[66:67]
	v_cvt_pk_bf16_f32 v106, v88, v89
	v_cvt_pk_bf16_f32 v107, v90, v91
	v_cvt_pk_bf16_f32 v108, v92, v93
	v_cvt_pk_bf16_f32 v109, v94, v95
	v_cvt_pk_bf16_f32 v110, v96, v97
	v_cvt_pk_bf16_f32 v111, v98, v99
	global_store_dwordx2 v2, v[106:107], s[6:7]
	global_store_dwordx2 v2, v[108:109], s[8:9]
	global_store_dwordx2 v2, v[110:111], s[10:11]
	s_add_u32 s6, s6, 0x1000
	s_addc_u32 s7, s7, 0
	s_add_u32 s8, s8, 0x1000
	s_addc_u32 s9, s9, 0
	s_add_u32 s10, s10, 0x1000
	s_addc_u32 s11, s11, 0
	s_waitcnt vmcnt(47)
	v_sub_f32_e32 v84, v64, v68
	v_sub_f32_e32 v85, v65, v69
	v_sub_f32_e32 v86, v66, v70
	v_sub_f32_e32 v87, v67, v71
	v_pk_fma_f32 v[88:89], v[84:85], v[4:5], v[68:69]
	v_pk_fma_f32 v[90:91], v[86:87], v[6:7], v[70:71]
	v_pk_fma_f32 v[92:93], v[84:85], v[8:9], v[68:69]
	v_pk_fma_f32 v[94:95], v[86:87], v[10:11], v[70:71]
	v_pk_fma_f32 v[96:97], v[84:85], v[12:13], v[68:69]
	v_pk_fma_f32 v[98:99], v[86:87], v[14:15], v[70:71]
	v_cvt_pk_bf16_f32 v100, v88, v89
	v_cvt_pk_bf16_f32 v101, v90, v91
	v_cvt_pk_bf16_f32 v102, v92, v93
	v_cvt_pk_bf16_f32 v103, v94, v95
	v_cvt_pk_bf16_f32 v104, v96, v97
	v_cvt_pk_bf16_f32 v105, v98, v99
	global_store_dwordx2 v2, v[100:101], s[6:7]
	global_store_dwordx2 v2, v[102:103], s[8:9]
	global_store_dwordx2 v2, v[104:105], s[10:11]
	s_add_u32 s6, s6, 0x1000
	s_addc_u32 s7, s7, 0
	s_add_u32 s8, s8, 0x1000
	s_addc_u32 s9, s9, 0
	s_add_u32 s10, s10, 0x1000
	s_addc_u32 s11, s11, 0
	s_waitcnt vmcnt(49)
	v_sub_f32_e32 v84, v68, v72
	v_sub_f32_e32 v85, v69, v73
	v_sub_f32_e32 v86, v70, v74
	v_sub_f32_e32 v87, v71, v75
	v_pk_fma_f32 v[88:89], v[84:85], v[4:5], v[72:73]
	v_pk_fma_f32 v[90:91], v[86:87], v[6:7], v[74:75]
	v_pk_fma_f32 v[92:93], v[84:85], v[8:9], v[72:73]
	v_pk_fma_f32 v[94:95], v[86:87], v[10:11], v[74:75]
	v_pk_fma_f32 v[96:97], v[84:85], v[12:13], v[72:73]
	v_pk_fma_f32 v[98:99], v[86:87], v[14:15], v[74:75]
	v_cvt_pk_bf16_f32 v106, v88, v89
	v_cvt_pk_bf16_f32 v107, v90, v91
	v_cvt_pk_bf16_f32 v108, v92, v93
	v_cvt_pk_bf16_f32 v109, v94, v95
	v_cvt_pk_bf16_f32 v110, v96, v97
	v_cvt_pk_bf16_f32 v111, v98, v99
	global_store_dwordx2 v2, v[106:107], s[6:7]
	global_store_dwordx2 v2, v[108:109], s[8:9]
	global_store_dwordx2 v2, v[110:111], s[10:11]
	s_add_u32 s6, s6, 0x1000
	s_addc_u32 s7, s7, 0
	s_add_u32 s8, s8, 0x1000
	s_addc_u32 s9, s9, 0
	s_add_u32 s10, s10, 0x1000
	s_addc_u32 s11, s11, 0
	s_waitcnt vmcnt(51)
	v_sub_f32_e32 v84, v72, v76
	v_sub_f32_e32 v85, v73, v77
	v_sub_f32_e32 v86, v74, v78
	v_sub_f32_e32 v87, v75, v79
	v_pk_fma_f32 v[88:89], v[84:85], v[4:5], v[76:77]
	v_pk_fma_f32 v[90:91], v[86:87], v[6:7], v[78:79]
	v_pk_fma_f32 v[92:93], v[84:85], v[8:9], v[76:77]
	v_pk_fma_f32 v[94:95], v[86:87], v[10:11], v[78:79]
	v_pk_fma_f32 v[96:97], v[84:85], v[12:13], v[76:77]
	v_pk_fma_f32 v[98:99], v[86:87], v[14:15], v[78:79]
	v_cvt_pk_bf16_f32 v100, v88, v89
	v_cvt_pk_bf16_f32 v101, v90, v91
	v_cvt_pk_bf16_f32 v102, v92, v93
	v_cvt_pk_bf16_f32 v103, v94, v95
	v_cvt_pk_bf16_f32 v104, v96, v97
	v_cvt_pk_bf16_f32 v105, v98, v99
	global_store_dwordx2 v2, v[100:101], s[6:7]
	global_store_dwordx2 v2, v[102:103], s[8:9]
	global_store_dwordx2 v2, v[104:105], s[10:11]
	s_add_u32 s6, s6, 0x1000
	s_addc_u32 s7, s7, 0
	s_add_u32 s8, s8, 0x1000
	s_addc_u32 s9, s9, 0
	s_add_u32 s10, s10, 0x1000
	s_addc_u32 s11, s11, 0
	s_waitcnt vmcnt(53)
	v_sub_f32_e32 v84, v76, v80
	v_sub_f32_e32 v85, v77, v81
	v_sub_f32_e32 v86, v78, v82
	v_sub_f32_e32 v87, v79, v83
	v_pk_fma_f32 v[88:89], v[84:85], v[4:5], v[80:81]
	v_pk_fma_f32 v[90:91], v[86:87], v[6:7], v[82:83]
	v_pk_fma_f32 v[92:93], v[84:85], v[8:9], v[80:81]
	v_pk_fma_f32 v[94:95], v[86:87], v[10:11], v[82:83]
	v_pk_fma_f32 v[96:97], v[84:85], v[12:13], v[80:81]
	v_pk_fma_f32 v[98:99], v[86:87], v[14:15], v[82:83]
	v_cvt_pk_bf16_f32 v106, v88, v89
	v_cvt_pk_bf16_f32 v107, v90, v91
	v_cvt_pk_bf16_f32 v108, v92, v93
	v_cvt_pk_bf16_f32 v109, v94, v95
	v_cvt_pk_bf16_f32 v110, v96, v97
	v_cvt_pk_bf16_f32 v111, v98, v99
	global_store_dwordx2 v2, v[106:107], s[6:7]
	global_store_dwordx2 v2, v[108:109], s[8:9]
	global_store_dwordx2 v2, v[110:111], s[10:11]
	s_add_u32 s6, s6, 0x1000
	s_addc_u32 s7, s7, 0
	s_add_u32 s8, s8, 0x1000
	s_addc_u32 s9, s9, 0
	s_add_u32 s10, s10, 0x1000
	s_addc_u32 s11, s11, 0
	v_mov_b32_e32 v16, v80
	v_mov_b32_e32 v17, v81
	v_mov_b32_e32 v18, v82
	v_mov_b32_e32 v19, v83
	global_load_dwordx4 v[52:55], v1, s[4:5]
	s_add_u32 s4, s4, 0x2000
	s_addc_u32 s5, s5, 0
	global_load_dwordx4 v[56:59], v1, s[4:5]
	s_add_u32 s4, s4, 0x2000
	s_addc_u32 s5, s5, 0
	global_load_dwordx4 v[60:63], v1, s[4:5]
	s_add_u32 s4, s4, 0x2000
	s_addc_u32 s5, s5, 0
	global_load_dwordx4 v[64:67], v1, s[4:5]
	s_add_u32 s4, s4, 0x2000
	s_addc_u32 s5, s5, 0
	global_load_dwordx4 v[68:71], v1, s[4:5]
	s_add_u32 s4, s4, 0x2000
	s_addc_u32 s5, s5, 0
	global_load_dwordx4 v[72:75], v1, s[4:5]
	s_add_u32 s4, s4, 0x2000
	s_addc_u32 s5, s5, 0
	global_load_dwordx4 v[76:79], v1, s[4:5]
	s_add_u32 s4, s4, 0x2000
	s_addc_u32 s5, s5, 0
	global_load_dwordx4 v[80:83], v1, s[4:5]
	s_add_u32 s4, s4, 0x2000
	s_addc_u32 s5, s5, 0
	s_waitcnt vmcnt(39)
	v_sub_f32_e32 v84, v16, v20
	v_sub_f32_e32 v85, v17, v21
	v_sub_f32_e32 v86, v18, v22
	v_sub_f32_e32 v87, v19, v23
	v_pk_fma_f32 v[88:89], v[84:85], v[4:5], v[20:21]
	v_pk_fma_f32 v[90:91], v[86:87], v[6:7], v[22:23]
	v_pk_fma_f32 v[92:93], v[84:85], v[8:9], v[20:21]
	v_pk_fma_f32 v[94:95], v[86:87], v[10:11], v[22:23]
	v_pk_fma_f32 v[96:97], v[84:85], v[12:13], v[20:21]
	v_pk_fma_f32 v[98:99], v[86:87], v[14:15], v[22:23]
	v_cvt_pk_bf16_f32 v100, v88, v89
	v_cvt_pk_bf16_f32 v101, v90, v91
	v_cvt_pk_bf16_f32 v102, v92, v93
	v_cvt_pk_bf16_f32 v103, v94, v95
	v_cvt_pk_bf16_f32 v104, v96, v97
	v_cvt_pk_bf16_f32 v105, v98, v99
	global_store_dwordx2 v2, v[100:101], s[6:7]
	global_store_dwordx2 v2, v[102:103], s[8:9]
	global_store_dwordx2 v2, v[104:105], s[10:11]
	s_add_u32 s6, s6, 0x1000
	s_addc_u32 s7, s7, 0
	s_add_u32 s8, s8, 0x1000
	s_addc_u32 s9, s9, 0
	s_add_u32 s10, s10, 0x1000
	s_addc_u32 s11, s11, 0
	s_waitcnt vmcnt(41)
	v_sub_f32_e32 v84, v20, v24
	v_sub_f32_e32 v85, v21, v25
	v_sub_f32_e32 v86, v22, v26
	v_sub_f32_e32 v87, v23, v27
	v_pk_fma_f32 v[88:89], v[84:85], v[4:5], v[24:25]
	v_pk_fma_f32 v[90:91], v[86:87], v[6:7], v[26:27]
	v_pk_fma_f32 v[92:93], v[84:85], v[8:9], v[24:25]
	v_pk_fma_f32 v[94:95], v[86:87], v[10:11], v[26:27]
	v_pk_fma_f32 v[96:97], v[84:85], v[12:13], v[24:25]
	v_pk_fma_f32 v[98:99], v[86:87], v[14:15], v[26:27]
	v_cvt_pk_bf16_f32 v106, v88, v89
	v_cvt_pk_bf16_f32 v107, v90, v91
	v_cvt_pk_bf16_f32 v108, v92, v93
	v_cvt_pk_bf16_f32 v109, v94, v95
	v_cvt_pk_bf16_f32 v110, v96, v97
	v_cvt_pk_bf16_f32 v111, v98, v99
	global_store_dwordx2 v2, v[106:107], s[6:7]
	global_store_dwordx2 v2, v[108:109], s[8:9]
	global_store_dwordx2 v2, v[110:111], s[10:11]
	s_add_u32 s6, s6, 0x1000
	s_addc_u32 s7, s7, 0
	s_add_u32 s8, s8, 0x1000
	s_addc_u32 s9, s9, 0
	s_add_u32 s10, s10, 0x1000
	s_addc_u32 s11, s11, 0
	s_waitcnt vmcnt(43)
	v_sub_f32_e32 v84, v24, v28
	v_sub_f32_e32 v85, v25, v29
	v_sub_f32_e32 v86, v26, v30
	v_sub_f32_e32 v87, v27, v31
	v_pk_fma_f32 v[88:89], v[84:85], v[4:5], v[28:29]
	v_pk_fma_f32 v[90:91], v[86:87], v[6:7], v[30:31]
	v_pk_fma_f32 v[92:93], v[84:85], v[8:9], v[28:29]
	v_pk_fma_f32 v[94:95], v[86:87], v[10:11], v[30:31]
	v_pk_fma_f32 v[96:97], v[84:85], v[12:13], v[28:29]
	v_pk_fma_f32 v[98:99], v[86:87], v[14:15], v[30:31]
	v_cvt_pk_bf16_f32 v100, v88, v89
	v_cvt_pk_bf16_f32 v101, v90, v91
	v_cvt_pk_bf16_f32 v102, v92, v93
	v_cvt_pk_bf16_f32 v103, v94, v95
	v_cvt_pk_bf16_f32 v104, v96, v97
	v_cvt_pk_bf16_f32 v105, v98, v99
	global_store_dwordx2 v2, v[100:101], s[6:7]
	global_store_dwordx2 v2, v[102:103], s[8:9]
	global_store_dwordx2 v2, v[104:105], s[10:11]
	s_add_u32 s6, s6, 0x1000
	s_addc_u32 s7, s7, 0
	s_add_u32 s8, s8, 0x1000
	s_addc_u32 s9, s9, 0
	s_add_u32 s10, s10, 0x1000
	s_addc_u32 s11, s11, 0
	s_waitcnt vmcnt(45)
	v_sub_f32_e32 v84, v28, v32
	v_sub_f32_e32 v85, v29, v33
	v_sub_f32_e32 v86, v30, v34
	v_sub_f32_e32 v87, v31, v35
	v_pk_fma_f32 v[88:89], v[84:85], v[4:5], v[32:33]
	v_pk_fma_f32 v[90:91], v[86:87], v[6:7], v[34:35]
	v_pk_fma_f32 v[92:93], v[84:85], v[8:9], v[32:33]
	v_pk_fma_f32 v[94:95], v[86:87], v[10:11], v[34:35]
	v_pk_fma_f32 v[96:97], v[84:85], v[12:13], v[32:33]
	v_pk_fma_f32 v[98:99], v[86:87], v[14:15], v[34:35]
	v_cvt_pk_bf16_f32 v106, v88, v89
	v_cvt_pk_bf16_f32 v107, v90, v91
	v_cvt_pk_bf16_f32 v108, v92, v93
	v_cvt_pk_bf16_f32 v109, v94, v95
	v_cvt_pk_bf16_f32 v110, v96, v97
	v_cvt_pk_bf16_f32 v111, v98, v99
	global_store_dwordx2 v2, v[106:107], s[6:7]
	global_store_dwordx2 v2, v[108:109], s[8:9]
	global_store_dwordx2 v2, v[110:111], s[10:11]
	s_add_u32 s6, s6, 0x1000
	s_addc_u32 s7, s7, 0
	s_add_u32 s8, s8, 0x1000
	s_addc_u32 s9, s9, 0
	s_add_u32 s10, s10, 0x1000
	s_addc_u32 s11, s11, 0
	s_waitcnt vmcnt(47)
	v_sub_f32_e32 v84, v32, v36
	v_sub_f32_e32 v85, v33, v37
	v_sub_f32_e32 v86, v34, v38
	v_sub_f32_e32 v87, v35, v39
	v_pk_fma_f32 v[88:89], v[84:85], v[4:5], v[36:37]
	v_pk_fma_f32 v[90:91], v[86:87], v[6:7], v[38:39]
	v_pk_fma_f32 v[92:93], v[84:85], v[8:9], v[36:37]
	v_pk_fma_f32 v[94:95], v[86:87], v[10:11], v[38:39]
	v_pk_fma_f32 v[96:97], v[84:85], v[12:13], v[36:37]
	v_pk_fma_f32 v[98:99], v[86:87], v[14:15], v[38:39]
	v_cvt_pk_bf16_f32 v100, v88, v89
	v_cvt_pk_bf16_f32 v101, v90, v91
	v_cvt_pk_bf16_f32 v102, v92, v93
	v_cvt_pk_bf16_f32 v103, v94, v95
	v_cvt_pk_bf16_f32 v104, v96, v97
	v_cvt_pk_bf16_f32 v105, v98, v99
	global_store_dwordx2 v2, v[100:101], s[6:7]
	global_store_dwordx2 v2, v[102:103], s[8:9]
	global_store_dwordx2 v2, v[104:105], s[10:11]
	s_add_u32 s6, s6, 0x1000
	s_addc_u32 s7, s7, 0
	s_add_u32 s8, s8, 0x1000
	s_addc_u32 s9, s9, 0
	s_add_u32 s10, s10, 0x1000
	s_addc_u32 s11, s11, 0
	s_waitcnt vmcnt(49)
	v_sub_f32_e32 v84, v36, v40
	v_sub_f32_e32 v85, v37, v41
	v_sub_f32_e32 v86, v38, v42
	v_sub_f32_e32 v87, v39, v43
	v_pk_fma_f32 v[88:89], v[84:85], v[4:5], v[40:41]
	v_pk_fma_f32 v[90:91], v[86:87], v[6:7], v[42:43]
	v_pk_fma_f32 v[92:93], v[84:85], v[8:9], v[40:41]
	v_pk_fma_f32 v[94:95], v[86:87], v[10:11], v[42:43]
	v_pk_fma_f32 v[96:97], v[84:85], v[12:13], v[40:41]
	v_pk_fma_f32 v[98:99], v[86:87], v[14:15], v[42:43]
	v_cvt_pk_bf16_f32 v106, v88, v89
	v_cvt_pk_bf16_f32 v107, v90, v91
	v_cvt_pk_bf16_f32 v108, v92, v93
	v_cvt_pk_bf16_f32 v109, v94, v95
	v_cvt_pk_bf16_f32 v110, v96, v97
	v_cvt_pk_bf16_f32 v111, v98, v99
	global_store_dwordx2 v2, v[106:107], s[6:7]
	global_store_dwordx2 v2, v[108:109], s[8:9]
	global_store_dwordx2 v2, v[110:111], s[10:11]
	s_add_u32 s6, s6, 0x1000
	s_addc_u32 s7, s7, 0
	s_add_u32 s8, s8, 0x1000
	s_addc_u32 s9, s9, 0
	s_add_u32 s10, s10, 0x1000
	s_addc_u32 s11, s11, 0
	s_waitcnt vmcnt(51)
	v_sub_f32_e32 v84, v40, v44
	v_sub_f32_e32 v85, v41, v45
	v_sub_f32_e32 v86, v42, v46
	v_sub_f32_e32 v87, v43, v47
	v_pk_fma_f32 v[88:89], v[84:85], v[4:5], v[44:45]
	v_pk_fma_f32 v[90:91], v[86:87], v[6:7], v[46:47]
	v_pk_fma_f32 v[92:93], v[84:85], v[8:9], v[44:45]
	v_pk_fma_f32 v[94:95], v[86:87], v[10:11], v[46:47]
	v_pk_fma_f32 v[96:97], v[84:85], v[12:13], v[44:45]
	v_pk_fma_f32 v[98:99], v[86:87], v[14:15], v[46:47]
	v_cvt_pk_bf16_f32 v100, v88, v89
	v_cvt_pk_bf16_f32 v101, v90, v91
	v_cvt_pk_bf16_f32 v102, v92, v93
	v_cvt_pk_bf16_f32 v103, v94, v95
	v_cvt_pk_bf16_f32 v104, v96, v97
	v_cvt_pk_bf16_f32 v105, v98, v99
	global_store_dwordx2 v2, v[100:101], s[6:7]
	global_store_dwordx2 v2, v[102:103], s[8:9]
	global_store_dwordx2 v2, v[104:105], s[10:11]
	s_add_u32 s6, s6, 0x1000
	s_addc_u32 s7, s7, 0
	s_add_u32 s8, s8, 0x1000
	s_addc_u32 s9, s9, 0
	s_add_u32 s10, s10, 0x1000
	s_addc_u32 s11, s11, 0
	s_waitcnt vmcnt(53)
	v_sub_f32_e32 v84, v44, v48
	v_sub_f32_e32 v85, v45, v49
	v_sub_f32_e32 v86, v46, v50
	v_sub_f32_e32 v87, v47, v51
	v_pk_fma_f32 v[88:89], v[84:85], v[4:5], v[48:49]
	v_pk_fma_f32 v[90:91], v[86:87], v[6:7], v[50:51]
	v_pk_fma_f32 v[92:93], v[84:85], v[8:9], v[48:49]
	v_pk_fma_f32 v[94:95], v[86:87], v[10:11], v[50:51]
	v_pk_fma_f32 v[96:97], v[84:85], v[12:13], v[48:49]
	v_pk_fma_f32 v[98:99], v[86:87], v[14:15], v[50:51]
	v_cvt_pk_bf16_f32 v106, v88, v89
	v_cvt_pk_bf16_f32 v107, v90, v91
	v_cvt_pk_bf16_f32 v108, v92, v93
	v_cvt_pk_bf16_f32 v109, v94, v95
	v_cvt_pk_bf16_f32 v110, v96, v97
	v_cvt_pk_bf16_f32 v111, v98, v99
	global_store_dwordx2 v2, v[106:107], s[6:7]
	global_store_dwordx2 v2, v[108:109], s[8:9]
	global_store_dwordx2 v2, v[110:111], s[10:11]
	s_add_u32 s6, s6, 0x1000
	s_addc_u32 s7, s7, 0
	s_add_u32 s8, s8, 0x1000
	s_addc_u32 s9, s9, 0
	s_add_u32 s10, s10, 0x1000
	s_addc_u32 s11, s11, 0
	v_mov_b32_e32 v16, v48
	v_mov_b32_e32 v17, v49
	v_mov_b32_e32 v18, v50
	v_mov_b32_e32 v19, v51
	s_waitcnt vmcnt(31)
	v_sub_f32_e32 v84, v16, v52
	v_sub_f32_e32 v85, v17, v53
	v_sub_f32_e32 v86, v18, v54
	v_sub_f32_e32 v87, v19, v55
	v_pk_fma_f32 v[88:89], v[84:85], v[4:5], v[52:53]
	v_pk_fma_f32 v[90:91], v[86:87], v[6:7], v[54:55]
	v_pk_fma_f32 v[92:93], v[84:85], v[8:9], v[52:53]
	v_pk_fma_f32 v[94:95], v[86:87], v[10:11], v[54:55]
	v_pk_fma_f32 v[96:97], v[84:85], v[12:13], v[52:53]
	v_pk_fma_f32 v[98:99], v[86:87], v[14:15], v[54:55]
	v_cvt_pk_bf16_f32 v100, v88, v89
	v_cvt_pk_bf16_f32 v101, v90, v91
	v_cvt_pk_bf16_f32 v102, v92, v93
	v_cvt_pk_bf16_f32 v103, v94, v95
	v_cvt_pk_bf16_f32 v104, v96, v97
	v_cvt_pk_bf16_f32 v105, v98, v99
	global_store_dwordx2 v2, v[100:101], s[6:7]
	global_store_dwordx2 v2, v[102:103], s[8:9]
	global_store_dwordx2 v2, v[104:105], s[10:11]
	s_add_u32 s6, s6, 0x1000
	s_addc_u32 s7, s7, 0
	s_add_u32 s8, s8, 0x1000
	s_addc_u32 s9, s9, 0
	s_add_u32 s10, s10, 0x1000
	s_addc_u32 s11, s11, 0
	s_waitcnt vmcnt(33)
	v_sub_f32_e32 v84, v52, v56
	v_sub_f32_e32 v85, v53, v57
	v_sub_f32_e32 v86, v54, v58
	v_sub_f32_e32 v87, v55, v59
	v_pk_fma_f32 v[88:89], v[84:85], v[4:5], v[56:57]
	v_pk_fma_f32 v[90:91], v[86:87], v[6:7], v[58:59]
	v_pk_fma_f32 v[92:93], v[84:85], v[8:9], v[56:57]
	v_pk_fma_f32 v[94:95], v[86:87], v[10:11], v[58:59]
	v_pk_fma_f32 v[96:97], v[84:85], v[12:13], v[56:57]
	v_pk_fma_f32 v[98:99], v[86:87], v[14:15], v[58:59]
	v_cvt_pk_bf16_f32 v106, v88, v89
	v_cvt_pk_bf16_f32 v107, v90, v91
	v_cvt_pk_bf16_f32 v108, v92, v93
	v_cvt_pk_bf16_f32 v109, v94, v95
	v_cvt_pk_bf16_f32 v110, v96, v97
	v_cvt_pk_bf16_f32 v111, v98, v99
	global_store_dwordx2 v2, v[106:107], s[6:7]
	global_store_dwordx2 v2, v[108:109], s[8:9]
	global_store_dwordx2 v2, v[110:111], s[10:11]
	s_add_u32 s6, s6, 0x1000
	s_addc_u32 s7, s7, 0
	s_add_u32 s8, s8, 0x1000
	s_addc_u32 s9, s9, 0
	s_add_u32 s10, s10, 0x1000
	s_addc_u32 s11, s11, 0
	s_waitcnt vmcnt(35)
	v_sub_f32_e32 v84, v56, v60
	v_sub_f32_e32 v85, v57, v61
	v_sub_f32_e32 v86, v58, v62
	v_sub_f32_e32 v87, v59, v63
	v_pk_fma_f32 v[88:89], v[84:85], v[4:5], v[60:61]
	v_pk_fma_f32 v[90:91], v[86:87], v[6:7], v[62:63]
	v_pk_fma_f32 v[92:93], v[84:85], v[8:9], v[60:61]
	v_pk_fma_f32 v[94:95], v[86:87], v[10:11], v[62:63]
	v_pk_fma_f32 v[96:97], v[84:85], v[12:13], v[60:61]
	v_pk_fma_f32 v[98:99], v[86:87], v[14:15], v[62:63]
	v_cvt_pk_bf16_f32 v100, v88, v89
	v_cvt_pk_bf16_f32 v101, v90, v91
	v_cvt_pk_bf16_f32 v102, v92, v93
	v_cvt_pk_bf16_f32 v103, v94, v95
	v_cvt_pk_bf16_f32 v104, v96, v97
	v_cvt_pk_bf16_f32 v105, v98, v99
	global_store_dwordx2 v2, v[100:101], s[6:7]
	global_store_dwordx2 v2, v[102:103], s[8:9]
	global_store_dwordx2 v2, v[104:105], s[10:11]
	s_add_u32 s6, s6, 0x1000
	s_addc_u32 s7, s7, 0
	s_add_u32 s8, s8, 0x1000
	s_addc_u32 s9, s9, 0
	s_add_u32 s10, s10, 0x1000
	s_addc_u32 s11, s11, 0
	s_waitcnt vmcnt(37)
	v_sub_f32_e32 v84, v60, v64
	v_sub_f32_e32 v85, v61, v65
	v_sub_f32_e32 v86, v62, v66
	v_sub_f32_e32 v87, v63, v67
	v_pk_fma_f32 v[88:89], v[84:85], v[4:5], v[64:65]
	v_pk_fma_f32 v[90:91], v[86:87], v[6:7], v[66:67]
	v_pk_fma_f32 v[92:93], v[84:85], v[8:9], v[64:65]
	v_pk_fma_f32 v[94:95], v[86:87], v[10:11], v[66:67]
	v_pk_fma_f32 v[96:97], v[84:85], v[12:13], v[64:65]
	v_pk_fma_f32 v[98:99], v[86:87], v[14:15], v[66:67]
	v_cvt_pk_bf16_f32 v106, v88, v89
	v_cvt_pk_bf16_f32 v107, v90, v91
	v_cvt_pk_bf16_f32 v108, v92, v93
	v_cvt_pk_bf16_f32 v109, v94, v95
	v_cvt_pk_bf16_f32 v110, v96, v97
	v_cvt_pk_bf16_f32 v111, v98, v99
	global_store_dwordx2 v2, v[106:107], s[6:7]
	global_store_dwordx2 v2, v[108:109], s[8:9]
	global_store_dwordx2 v2, v[110:111], s[10:11]
	s_add_u32 s6, s6, 0x1000
	s_addc_u32 s7, s7, 0
	s_add_u32 s8, s8, 0x1000
	s_addc_u32 s9, s9, 0
	s_add_u32 s10, s10, 0x1000
	s_addc_u32 s11, s11, 0
	s_waitcnt vmcnt(39)
	v_sub_f32_e32 v84, v64, v68
	v_sub_f32_e32 v85, v65, v69
	v_sub_f32_e32 v86, v66, v70
	v_sub_f32_e32 v87, v67, v71
	v_pk_fma_f32 v[88:89], v[84:85], v[4:5], v[68:69]
	v_pk_fma_f32 v[90:91], v[86:87], v[6:7], v[70:71]
	v_pk_fma_f32 v[92:93], v[84:85], v[8:9], v[68:69]
	v_pk_fma_f32 v[94:95], v[86:87], v[10:11], v[70:71]
	v_pk_fma_f32 v[96:97], v[84:85], v[12:13], v[68:69]
	v_pk_fma_f32 v[98:99], v[86:87], v[14:15], v[70:71]
	v_cvt_pk_bf16_f32 v100, v88, v89
	v_cvt_pk_bf16_f32 v101, v90, v91
	v_cvt_pk_bf16_f32 v102, v92, v93
	v_cvt_pk_bf16_f32 v103, v94, v95
	v_cvt_pk_bf16_f32 v104, v96, v97
	v_cvt_pk_bf16_f32 v105, v98, v99
	global_store_dwordx2 v2, v[100:101], s[6:7]
	global_store_dwordx2 v2, v[102:103], s[8:9]
	global_store_dwordx2 v2, v[104:105], s[10:11]
	s_add_u32 s6, s6, 0x1000
	s_addc_u32 s7, s7, 0
	s_add_u32 s8, s8, 0x1000
	s_addc_u32 s9, s9, 0
	s_add_u32 s10, s10, 0x1000
	s_addc_u32 s11, s11, 0
	s_waitcnt vmcnt(41)
	v_sub_f32_e32 v84, v68, v72
	v_sub_f32_e32 v85, v69, v73
	v_sub_f32_e32 v86, v70, v74
	v_sub_f32_e32 v87, v71, v75
	v_pk_fma_f32 v[88:89], v[84:85], v[4:5], v[72:73]
	v_pk_fma_f32 v[90:91], v[86:87], v[6:7], v[74:75]
	v_pk_fma_f32 v[92:93], v[84:85], v[8:9], v[72:73]
	v_pk_fma_f32 v[94:95], v[86:87], v[10:11], v[74:75]
	v_pk_fma_f32 v[96:97], v[84:85], v[12:13], v[72:73]
	v_pk_fma_f32 v[98:99], v[86:87], v[14:15], v[74:75]
	v_cvt_pk_bf16_f32 v106, v88, v89
	v_cvt_pk_bf16_f32 v107, v90, v91
	v_cvt_pk_bf16_f32 v108, v92, v93
	v_cvt_pk_bf16_f32 v109, v94, v95
	v_cvt_pk_bf16_f32 v110, v96, v97
	v_cvt_pk_bf16_f32 v111, v98, v99
	global_store_dwordx2 v2, v[106:107], s[6:7]
	global_store_dwordx2 v2, v[108:109], s[8:9]
	global_store_dwordx2 v2, v[110:111], s[10:11]
	s_add_u32 s6, s6, 0x1000
	s_addc_u32 s7, s7, 0
	s_add_u32 s8, s8, 0x1000
	s_addc_u32 s9, s9, 0
	s_add_u32 s10, s10, 0x1000
	s_addc_u32 s11, s11, 0
	s_waitcnt vmcnt(43)
	v_sub_f32_e32 v84, v72, v76
	v_sub_f32_e32 v85, v73, v77
	v_sub_f32_e32 v86, v74, v78
	v_sub_f32_e32 v87, v75, v79
	v_pk_fma_f32 v[88:89], v[84:85], v[4:5], v[76:77]
	v_pk_fma_f32 v[90:91], v[86:87], v[6:7], v[78:79]
	v_pk_fma_f32 v[92:93], v[84:85], v[8:9], v[76:77]
	v_pk_fma_f32 v[94:95], v[86:87], v[10:11], v[78:79]
	v_pk_fma_f32 v[96:97], v[84:85], v[12:13], v[76:77]
	v_pk_fma_f32 v[98:99], v[86:87], v[14:15], v[78:79]
	v_cvt_pk_bf16_f32 v100, v88, v89
	v_cvt_pk_bf16_f32 v101, v90, v91
	v_cvt_pk_bf16_f32 v102, v92, v93
	v_cvt_pk_bf16_f32 v103, v94, v95
	v_cvt_pk_bf16_f32 v104, v96, v97
	v_cvt_pk_bf16_f32 v105, v98, v99
	global_store_dwordx2 v2, v[100:101], s[6:7]
	global_store_dwordx2 v2, v[102:103], s[8:9]
	global_store_dwordx2 v2, v[104:105], s[10:11]
	s_add_u32 s6, s6, 0x1000
	s_addc_u32 s7, s7, 0
	s_add_u32 s8, s8, 0x1000
	s_addc_u32 s9, s9, 0
	s_add_u32 s10, s10, 0x1000
	s_addc_u32 s11, s11, 0
	s_waitcnt vmcnt(45)
	v_sub_f32_e32 v84, v76, v80
	v_sub_f32_e32 v85, v77, v81
	v_sub_f32_e32 v86, v78, v82
	v_sub_f32_e32 v87, v79, v83
	v_pk_fma_f32 v[88:89], v[84:85], v[4:5], v[80:81]
	v_pk_fma_f32 v[90:91], v[86:87], v[6:7], v[82:83]
	v_pk_fma_f32 v[92:93], v[84:85], v[8:9], v[80:81]
	v_pk_fma_f32 v[94:95], v[86:87], v[10:11], v[82:83]
	v_pk_fma_f32 v[96:97], v[84:85], v[12:13], v[80:81]
	v_pk_fma_f32 v[98:99], v[86:87], v[14:15], v[82:83]
	v_cvt_pk_bf16_f32 v106, v88, v89
	v_cvt_pk_bf16_f32 v107, v90, v91
	v_cvt_pk_bf16_f32 v108, v92, v93
	v_cvt_pk_bf16_f32 v109, v94, v95
	v_cvt_pk_bf16_f32 v110, v96, v97
	v_cvt_pk_bf16_f32 v111, v98, v99
	global_store_dwordx2 v2, v[106:107], s[6:7]
	global_store_dwordx2 v2, v[108:109], s[8:9]
	global_store_dwordx2 v2, v[110:111], s[10:11]
	s_add_u32 s6, s6, 0x1000
	s_addc_u32 s7, s7, 0
	s_add_u32 s8, s8, 0x1000
	s_addc_u32 s9, s9, 0
	s_add_u32 s10, s10, 0x1000
	s_addc_u32 s11, s11, 0
	v_mov_b32_e32 v16, v80
	v_mov_b32_e32 v17, v81
	v_mov_b32_e32 v18, v82
	v_mov_b32_e32 v19, v83
	s_branch .LBB0_230
.Lmix2_orig:
	s_mov_b64 s[4:5], s[0:1]
	s_mov_b64 s[6:7], s[0:1]
	s_mov_b64 s[10:11], s[0:1]
	v_mov_b32_e32 v1, v190
	s_mov_b32 s8, s2
	s_lshl_b32 s8, s8, 9
	v_readfirstlane_b32 s3, v1
	s_andn2_b32 s3, s3, 63
	s_add_i32 s8, s8, s3
	v_and_or_b32 v10, v1, 63, s8
	s_mov_b32 s3, 0x800000
	v_cmp_gt_i32_e32 vcc, s3, v10
	s_and_saveexec_b64 s[8:9], vcc
	s_cbranch_execz .LBB0_229
	s_load_dwordx2 s[16:17], s[6:7], 0x8
	s_load_dwordx2 s[18:19], s[4:5], 0x0
	s_load_dwordx2 s[20:21], s[10:11], 0xe0
	s_lshl_b32 s10, s24, 9
	v_ashrrev_i32_e32 v11, 31, v10
	s_waitcnt lgkmcnt(0)
	s_add_u32 s12, s16, 0x2000
	s_addc_u32 s13, s17, 0
	s_add_u32 s14, s16, 0x8000
	s_addc_u32 s15, s17, 0
	s_add_u32 s16, s16, 0xa000
	s_addc_u32 s17, s17, 0
	s_ashr_i32 s11, s10, 31
	v_lshl_add_u64 v[2:3], v[10:11], 3, s[20:21]
	s_mov_b64 s[4:5], 0x8100000
	v_lshl_add_u64 v[12:13], v[10:11], 4, s[18:19]
	s_lshl_b64 s[18:19], s[10:11], 4
	v_lshl_add_u64 v[14:15], v[2:3], 0, s[4:5]
	s_lshl_b64 s[20:21], s[10:11], 3
	s_mov_b64 s[22:23], 0
	s_brev_b32 s3, 32
	s_mov_b32 s11, 0x7fffff
	s_branch .LBB0_227
